# EpiConv: all 16 conv weight/bias vector loads prefetched at epilogue start (waits for groups 3-4 removed, no store-ack stalls)
# speedup vs baseline: 1.0366x; 1.0028x over previous
; #define PG8_STAGE(bufoff, gbase, voff) do { _Pragma("unroll") for (int _i = 0; _i < 2; ++_i) \
;         __builtin_amdgcn_global_load_lds((const unsigned*)((const char*)(gbase) + (voff)[_i]), (LAS unsigned*)(lds + (bufoff) + ldsw + _i * 8192), 16, 0, 0); } while (0)
; #define PG8_LDA(dst, b, h) do { _Pragma("unroll") for (int m = 0; m < 4; ++m) _Pragma("unroll") for (int k = 0; k < 2; ++k) dst[m][k] = *(const LAS bf16x8*)(lds + PG8_SA(b, h) + aoff + m * 2048 + k * 1024); } while (0)
; #define PG8_LDB(dst, b, h) do { _Pragma("unroll") for (int n = 0; n < 2; ++n) _Pragma("unroll") for (int k = 0; k < 2; ++k) dst[n][k] = *(const LAS bf16x8*)(lds + PG8_SB(b, h) + boff + n * 2048 + k * 1024); } while (0)
; #define PG8_MMA(ai, bj, At, Bt) do { __builtin_amdgcn_s_setprio(1); _Pragma("unroll") for (int m = 0; m < 4; ++m) _Pragma("unroll") for (int n = 0; n < 2; ++n) _Pragma("unroll") for (int k = 0; k < 2; ++k) \
;         acc[ai][bj][m][n] = __builtin_amdgcn_mfma_f32_16x16x32_bf16(Bt[n][k], At[m][k], acc[ai][bj][m][n], 0, 0, 0); __builtin_amdgcn_s_setprio(0); } while (0)
; #define PG8_WAIT_V(n) asm volatile("s_waitcnt vmcnt(" #n ")" ::: "memory")
; #define PG8_WAIT_L(n) asm volatile("s_waitcnt lgkmcnt(" #n ")" ::: "memory")
; #define PG8_BAR __builtin_amdgcn_s_barrier()
; #define PG8_SCHED __builtin_amdgcn_sched_barrier(0)
; template <class Epi, class SchedT>
; DI void gemm_phase(LAS unsigned char* lds, const Gemm g, const SchedT& S, const Epi& E) {
;     ...
;             PG8_LDB(B0, 0, 0); PG8_SCHED; PG8_LDA(At, 0, 0); PG8_STAGE(PG8_SA(1, 1), a1 + hstepA, voffA);
;             PG8_WAIT_L(8); PG8_BAR; PG8_WAIT_L(0); PG8_MMA(0, 0, At, B0); PG8_BAR; PG8_SCHED;
;             PG8_LDB(B1, 0, 1); PG8_STAGE(PG8_SB(0, 0), b2, voffB);
;             PG8_BAR; PG8_WAIT_L(0); PG8_MMA(0, 1, At, B1); PG8_BAR;
;             PG8_LDA(At, 0, 1); PG8_STAGE(PG8_SA(0, 0), a2, voffA);
;             PG8_BAR; PG8_WAIT_L(0); PG8_MMA(1, 0, At, B0); PG8_BAR; PG8_SCHED;
;             PG8_STAGE(PG8_SB(0, 1), b2 + hstepB, voffB);
;             PG8_WAIT_V(6); PG8_BAR; PG8_MMA(1, 1, At, B1); PG8_BAR;
.LBB0_1601:
	s_add_u32 s6, s0, 0xfffc0080
	s_addc_u32 s7, s1, -1
	s_add_i32 s15, 0, 0x10000
	v_add_u32_e32 v148, s15, v186
	ds_read_b128 v[136:139], v148
	ds_read_b128 v[140:143], v148 offset:1024
	ds_read_b128 v[144:147], v148 offset:2048
	ds_read_b128 v[148:151], v148 offset:3072
	s_cmp_eq_u32 s14, 28
	s_cselect_b32 s9, s41, s7
	s_cselect_b32 s8, s40, s6
	s_cselect_b32 s7, s5, s13
	s_cselect_b32 s6, s11, s12
	v_lshl_add_u64 v[180:181], s[0:1], 0, v[0:1]
	s_add_i32 m0, s81, 0xc000
	ds_read_b128 v[152:155], v187
	ds_read_b128 v[156:159], v187 offset:1024
	ds_read_b128 v[160:163], v187 offset:2048
	ds_read_b128 v[164:167], v187 offset:3072
	ds_read_b128 v[168:171], v187 offset:4096
	ds_read_b128 v[172:175], v187 offset:5120
	ds_read_b128 v[176:179], v187 offset:6144
	ds_read_b128 v[188:191], v187 offset:7168
	global_load_lds_dwordx4 v[180:181], off
	v_lshl_add_u64 v[180:181], s[0:1], 0, v[132:133]
	s_add_i32 m0, s81, 0xe000
	s_nop 0
	global_load_lds_dwordx4 v[180:181], off
	s_waitcnt lgkmcnt(8)
	s_barrier
	s_waitcnt lgkmcnt(0)
	s_setprio 1
	s_waitcnt lgkmcnt(0)
	v_mfma_f32_16x16x32_bf16 v[126:129], v[136:139], v[152:155], v[126:129]
	v_mfma_f32_16x16x32_bf16 v[62:65], v[144:147], v[152:155], v[62:65]
	v_mfma_f32_16x16x32_bf16 v[122:125], v[136:139], v[160:163], v[122:125]
	v_mfma_f32_16x16x32_bf16 v[58:61], v[144:147], v[160:163], v[58:61]
	v_mfma_f32_16x16x32_bf16 v[118:121], v[136:139], v[168:171], v[118:121]
	v_mfma_f32_16x16x32_bf16 v[54:57], v[144:147], v[168:171], v[54:57]
	v_mfma_f32_16x16x32_bf16 v[114:117], v[136:139], v[176:179], v[114:117]
	v_mfma_f32_16x16x32_bf16 v[50:53], v[144:147], v[176:179], v[50:53]
	v_mfma_f32_16x16x32_bf16 v[126:129], v[140:143], v[156:159], v[126:129]
	v_mfma_f32_16x16x32_bf16 v[62:65], v[148:151], v[156:159], v[62:65]
	v_mfma_f32_16x16x32_bf16 v[122:125], v[140:143], v[164:167], v[122:125]
	v_mfma_f32_16x16x32_bf16 v[58:61], v[148:151], v[164:167], v[58:61]
	v_mfma_f32_16x16x32_bf16 v[118:121], v[140:143], v[172:175], v[118:121]
	v_mfma_f32_16x16x32_bf16 v[54:57], v[148:151], v[172:175], v[54:57]
	v_mfma_f32_16x16x32_bf16 v[114:117], v[140:143], v[188:191], v[114:117]
	v_mfma_f32_16x16x32_bf16 v[50:53], v[148:151], v[188:191], v[50:53]
	s_setprio 0
	s_barrier
	s_add_i32 s18, 0, 0x14000
	v_add_u32_e32 v180, s18, v186
	s_add_i32 s15, s15, s76
	ds_read_b128 v[202:205], v180
	ds_read_b128 v[206:209], v180 offset:1024
	ds_read_b128 v[210:213], v180 offset:2048
	ds_read_b128 v[214:217], v180 offset:3072
	v_lshl_add_u64 v[180:181], s[6:7], 0, v[130:131]
	s_mov_b32 m0, s15
	v_lshl_add_u64 v[182:183], s[6:7], 0, v[134:135]
	global_load_lds_dwordx4 v[180:181], off
	s_add_i32 m0, s15, 0x2000
	s_nop 0
	global_load_lds_dwordx4 v[182:183], off
	s_barrier
	s_waitcnt lgkmcnt(0)
	s_setprio 1
	s_waitcnt lgkmcnt(0)
	v_mfma_f32_16x16x32_bf16 v[94:97], v[202:205], v[152:155], v[94:97]
	v_mfma_f32_16x16x32_bf16 v[30:33], v[210:213], v[152:155], v[30:33]
	v_mfma_f32_16x16x32_bf16 v[90:93], v[202:205], v[160:163], v[90:93]
	v_mfma_f32_16x16x32_bf16 v[26:29], v[210:213], v[160:163], v[26:29]
	v_mfma_f32_16x16x32_bf16 v[86:89], v[202:205], v[168:171], v[86:89]
	v_mfma_f32_16x16x32_bf16 v[22:25], v[210:213], v[168:171], v[22:25]
	v_mfma_f32_16x16x32_bf16 v[82:85], v[202:205], v[176:179], v[82:85]
	v_mfma_f32_16x16x32_bf16 v[18:21], v[210:213], v[176:179], v[18:21]
	v_mfma_f32_16x16x32_bf16 v[94:97], v[206:209], v[156:159], v[94:97]
	v_mfma_f32_16x16x32_bf16 v[30:33], v[214:217], v[156:159], v[30:33]
	v_mfma_f32_16x16x32_bf16 v[90:93], v[206:209], v[164:167], v[90:93]
	v_mfma_f32_16x16x32_bf16 v[26:29], v[214:217], v[164:167], v[26:29]
	v_mfma_f32_16x16x32_bf16 v[86:89], v[206:209], v[172:175], v[86:89]
	v_mfma_f32_16x16x32_bf16 v[22:25], v[214:217], v[172:175], v[22:25]
	v_mfma_f32_16x16x32_bf16 v[82:85], v[206:209], v[188:191], v[82:85]
	v_mfma_f32_16x16x32_bf16 v[18:21], v[214:217], v[188:191], v[18:21]
	s_setprio 0
	s_mov_b32 m0, s81
	v_lshl_add_u64 v[194:195], s[8:9], 0, v[0:1]
	s_barrier
	ds_read_b128 v[152:155], v187 offset:16384
	ds_read_b128 v[156:159], v187 offset:17408
	ds_read_b128 v[160:163], v187 offset:18432
	ds_read_b128 v[164:167], v187 offset:19456
	ds_read_b128 v[168:171], v187 offset:20480
	ds_read_b128 v[172:175], v187 offset:21504
	ds_read_b128 v[176:179], v187 offset:22528
	ds_read_b128 v[188:191], v187 offset:23552
	global_load_lds_dwordx4 v[194:195], off
	v_lshl_add_u64 v[196:197], s[8:9], 0, v[132:133]
	s_mov_b32 m0, s82
	s_nop 0
	global_load_lds_dwordx4 v[196:197], off
	s_barrier
	s_waitcnt lgkmcnt(0)
	s_setprio 1
	s_waitcnt lgkmcnt(0)
	v_mfma_f32_16x16x32_bf16 v[110:113], v[136:139], v[152:155], v[110:113]
	v_mfma_f32_16x16x32_bf16 v[46:49], v[144:147], v[152:155], v[46:49]
	v_mfma_f32_16x16x32_bf16 v[106:109], v[136:139], v[160:163], v[106:109]
	v_mfma_f32_16x16x32_bf16 v[42:45], v[144:147], v[160:163], v[42:45]
	v_mfma_f32_16x16x32_bf16 v[102:105], v[136:139], v[168:171], v[102:105]
	v_mfma_f32_16x16x32_bf16 v[38:41], v[144:147], v[168:171], v[38:41]
	v_mfma_f32_16x16x32_bf16 v[98:101], v[136:139], v[176:179], v[98:101]
	v_mfma_f32_16x16x32_bf16 v[34:37], v[144:147], v[176:179], v[34:37]
	v_mfma_f32_16x16x32_bf16 v[110:113], v[140:143], v[156:159], v[110:113]
	v_mfma_f32_16x16x32_bf16 v[46:49], v[148:151], v[156:159], v[46:49]
	v_mfma_f32_16x16x32_bf16 v[106:109], v[140:143], v[164:167], v[106:109]
	v_mfma_f32_16x16x32_bf16 v[42:45], v[148:151], v[164:167], v[42:45]
	v_mfma_f32_16x16x32_bf16 v[102:105], v[140:143], v[172:175], v[102:105]
	v_mfma_f32_16x16x32_bf16 v[38:41], v[148:151], v[172:175], v[38:41]
	v_mfma_f32_16x16x32_bf16 v[98:101], v[140:143], v[188:191], v[98:101]
	v_mfma_f32_16x16x32_bf16 v[34:37], v[148:151], v[188:191], v[34:37]
	s_setprio 0
	s_barrier
; #define PG8_STAGE(bufoff, gbase, voff) do { _Pragma("unroll") for (int _i = 0; _i < 2; ++_i) \
;         __builtin_amdgcn_global_load_lds((const unsigned*)((const char*)(gbase) + (voff)[_i]), (LAS unsigned*)(lds + (bufoff) + ldsw + _i * 8192), 16, 0, 0); } while (0)
; #define PG8_LDA(dst, b, h) do { _Pragma("unroll") for (int m = 0; m < 4; ++m) _Pragma("unroll") for (int k = 0; k < 2; ++k) dst[m][k] = *(const LAS bf16x8*)(lds + PG8_SA(b, h) + aoff + m * 2048 + k * 1024); } while (0)
; #define PG8_LDB(dst, b, h) do { _Pragma("unroll") for (int n = 0; n < 2; ++n) _Pragma("unroll") for (int k = 0; k < 2; ++k) dst[n][k] = *(const LAS bf16x8*)(lds + PG8_SB(b, h) + boff + n * 2048 + k * 1024); } while (0)
; #define PG8_MMA(ai, bj, At, Bt) do { __builtin_amdgcn_s_setprio(1); _Pragma("unroll") for (int m = 0; m < 4; ++m) _Pragma("unroll") for (int n = 0; n < 2; ++n) _Pragma("unroll") for (int k = 0; k < 2; ++k) \
;         acc[ai][bj][m][n] = __builtin_amdgcn_mfma_f32_16x16x32_bf16(Bt[n][k], At[m][k], acc[ai][bj][m][n], 0, 0, 0); __builtin_amdgcn_s_setprio(0); } while (0)
; #define PG8_WAIT_V(n) asm volatile("s_waitcnt vmcnt(" #n ")" ::: "memory")
; #define PG8_WAIT_L(n) asm volatile("s_waitcnt lgkmcnt(" #n ")" ::: "memory")
; #define PG8_BAR __builtin_amdgcn_s_barrier()
; #define PG8_SCHED __builtin_amdgcn_sched_barrier(0)
; template <class Epi, class SchedT>
; DI void gemm_phase(LAS unsigned char* lds, const Gemm g, const SchedT& S, const Epi& E) {
;     ...
;             PG8_STAGE(PG8_SB(0, 1), b2 + hstepB, voffB);
;             PG8_WAIT_V(6); PG8_BAR; PG8_MMA(1, 1, At, B1); PG8_BAR;
;             PG8_LDB(B0, 1, 0); PG8_SCHED; PG8_LDA(At, 1, 0); PG8_STAGE(PG8_SA(0, 1), a2 + hstepA, voffA);
;             PG8_WAIT_L(8); PG8_BAR; PG8_WAIT_L(0); PG8_MMA(0, 0, At, B0); PG8_BAR; PG8_SCHED;
;             PG8_LDB(B1, 1, 1); PG8_STAGE(PG8_SB(1, 0), b3, voffB);
;             PG8_BAR; PG8_WAIT_L(0); PG8_MMA(0, 1, At, B1); PG8_BAR;
;             PG8_LDA(At, 1, 1); PG8_STAGE(PG8_SA(1, 0), a3, voffA);
	s_add_u32 s16, s6, 0x80000
	s_addc_u32 s17, s7, 0
	s_add_i32 s15, s18, s76
	v_lshl_add_u64 v[136:137], s[16:17], 0, v[130:131]
	s_mov_b32 m0, s15
	s_nop 0
	global_load_lds_dwordx4 v[136:137], off
	v_lshl_add_u64 v[136:137], s[16:17], 0, v[134:135]
	s_add_i32 m0, s15, 0x2000
	s_nop 0
	global_load_lds_dwordx4 v[136:137], off
	s_waitcnt vmcnt(6)
	s_barrier
	s_setprio 1
	v_mfma_f32_16x16x32_bf16 v[78:81], v[202:205], v[152:155], v[78:81]
	v_mfma_f32_16x16x32_bf16 v[14:17], v[210:213], v[152:155], v[14:17]
	v_mfma_f32_16x16x32_bf16 v[74:77], v[202:205], v[160:163], v[74:77]
	v_mfma_f32_16x16x32_bf16 v[10:13], v[210:213], v[160:163], v[10:13]
	v_mfma_f32_16x16x32_bf16 v[70:73], v[202:205], v[168:171], v[70:73]
	v_mfma_f32_16x16x32_bf16 v[6:9], v[210:213], v[168:171], v[6:9]
	v_mfma_f32_16x16x32_bf16 v[66:69], v[202:205], v[176:179], v[66:69]
	v_mfma_f32_16x16x32_bf16 v[2:5], v[210:213], v[176:179], v[2:5]
	v_mfma_f32_16x16x32_bf16 v[78:81], v[206:209], v[156:159], v[78:81]
	v_mfma_f32_16x16x32_bf16 v[14:17], v[214:217], v[156:159], v[14:17]
	v_mfma_f32_16x16x32_bf16 v[74:77], v[206:209], v[164:167], v[74:77]
	v_mfma_f32_16x16x32_bf16 v[10:13], v[214:217], v[164:167], v[10:13]
	v_mfma_f32_16x16x32_bf16 v[70:73], v[206:209], v[172:175], v[70:73]
	v_mfma_f32_16x16x32_bf16 v[6:9], v[214:217], v[172:175], v[6:9]
	v_mfma_f32_16x16x32_bf16 v[66:69], v[206:209], v[188:191], v[66:69]
	v_mfma_f32_16x16x32_bf16 v[2:5], v[214:217], v[188:191], v[2:5]
	s_setprio 0
	s_add_i32 s15, 0, 0x18000
	v_add_u32_e32 v148, s15, v186
	s_barrier
	ds_read_b128 v[136:139], v148
	ds_read_b128 v[140:143], v148 offset:1024
	ds_read_b128 v[144:147], v148 offset:2048
	ds_read_b128 v[148:151], v148 offset:3072
	s_add_u32 s8, s8, 0x40000
	s_addc_u32 s9, s9, 0
	s_mov_b32 m0, s83
	v_lshl_add_u64 v[198:199], s[8:9], 0, v[0:1]
	ds_read_b128 v[152:155], v187 offset:32768
	ds_read_b128 v[156:159], v187 offset:33792
	ds_read_b128 v[160:163], v187 offset:34816
	ds_read_b128 v[164:167], v187 offset:35840
	ds_read_b128 v[168:171], v187 offset:36864
	ds_read_b128 v[172:175], v187 offset:37888
	ds_read_b128 v[176:179], v187 offset:38912
	ds_read_b128 v[188:191], v187 offset:39936
	global_load_lds_dwordx4 v[198:199], off
	v_lshl_add_u64 v[198:199], s[8:9], 0, v[132:133]
	s_mov_b32 m0, s88
	s_nop 0
	global_load_lds_dwordx4 v[198:199], off
	s_waitcnt lgkmcnt(8)
	s_barrier
	s_waitcnt lgkmcnt(0)
	s_setprio 1
	s_waitcnt lgkmcnt(0)
	v_mfma_f32_16x16x32_bf16 v[126:129], v[136:139], v[152:155], v[126:129]
	v_mfma_f32_16x16x32_bf16 v[62:65], v[144:147], v[152:155], v[62:65]
	v_mfma_f32_16x16x32_bf16 v[122:125], v[136:139], v[160:163], v[122:125]
	v_mfma_f32_16x16x32_bf16 v[58:61], v[144:147], v[160:163], v[58:61]
	v_mfma_f32_16x16x32_bf16 v[118:121], v[136:139], v[168:171], v[118:121]
	v_mfma_f32_16x16x32_bf16 v[54:57], v[144:147], v[168:171], v[54:57]
	v_mfma_f32_16x16x32_bf16 v[114:117], v[136:139], v[176:179], v[114:117]
	v_mfma_f32_16x16x32_bf16 v[50:53], v[144:147], v[176:179], v[50:53]
	v_mfma_f32_16x16x32_bf16 v[126:129], v[140:143], v[156:159], v[126:129]
	v_mfma_f32_16x16x32_bf16 v[62:65], v[148:151], v[156:159], v[62:65]
	v_mfma_f32_16x16x32_bf16 v[122:125], v[140:143], v[164:167], v[122:125]
	v_mfma_f32_16x16x32_bf16 v[58:61], v[148:151], v[164:167], v[58:61]
	v_mfma_f32_16x16x32_bf16 v[118:121], v[140:143], v[172:175], v[118:121]
	v_mfma_f32_16x16x32_bf16 v[54:57], v[148:151], v[172:175], v[54:57]
	v_mfma_f32_16x16x32_bf16 v[114:117], v[140:143], v[188:191], v[114:117]
	v_mfma_f32_16x16x32_bf16 v[50:53], v[148:151], v[188:191], v[50:53]
	s_setprio 0
	s_barrier
	s_add_i32 s8, 0, 0x1c000
	s_add_i32 s9, s15, s76
	v_add_u32_e32 v198, s8, v186
	v_lshl_add_u64 v[180:181], v[180:181], 0, s[90:91]
	s_mov_b32 m0, s9
	ds_read_b128 v[202:205], v198
	ds_read_b128 v[206:209], v198 offset:1024
	ds_read_b128 v[210:213], v198 offset:2048
	ds_read_b128 v[214:217], v198 offset:3072
	global_load_lds_dwordx4 v[180:181], off
	v_lshl_add_u64 v[180:181], v[182:183], 0, s[90:91]
	s_add_i32 m0, s9, 0x2000
	s_nop 0
	global_load_lds_dwordx4 v[180:181], off
	s_barrier
	s_waitcnt lgkmcnt(0)
	s_setprio 1
	s_waitcnt lgkmcnt(0)
	v_mfma_f32_16x16x32_bf16 v[94:97], v[202:205], v[152:155], v[94:97]
	v_mfma_f32_16x16x32_bf16 v[30:33], v[210:213], v[152:155], v[30:33]
	v_mfma_f32_16x16x32_bf16 v[90:93], v[202:205], v[160:163], v[90:93]
	v_mfma_f32_16x16x32_bf16 v[26:29], v[210:213], v[160:163], v[26:29]
	v_mfma_f32_16x16x32_bf16 v[86:89], v[202:205], v[168:171], v[86:89]
	v_mfma_f32_16x16x32_bf16 v[22:25], v[210:213], v[168:171], v[22:25]
	v_mfma_f32_16x16x32_bf16 v[82:85], v[202:205], v[176:179], v[82:85]
	v_mfma_f32_16x16x32_bf16 v[18:21], v[210:213], v[176:179], v[18:21]
	v_mfma_f32_16x16x32_bf16 v[94:97], v[206:209], v[156:159], v[94:97]
	v_mfma_f32_16x16x32_bf16 v[30:33], v[214:217], v[156:159], v[30:33]
	v_mfma_f32_16x16x32_bf16 v[90:93], v[206:209], v[164:167], v[90:93]
	v_mfma_f32_16x16x32_bf16 v[26:29], v[214:217], v[164:167], v[26:29]
	v_mfma_f32_16x16x32_bf16 v[86:89], v[206:209], v[172:175], v[86:89]
	v_mfma_f32_16x16x32_bf16 v[22:25], v[214:217], v[172:175], v[22:25]
	v_mfma_f32_16x16x32_bf16 v[82:85], v[206:209], v[188:191], v[82:85]
	v_mfma_f32_16x16x32_bf16 v[18:21], v[214:217], v[188:191], v[18:21]
	s_setprio 0
	s_mov_b32 m0, s47
	v_lshl_add_u64 v[180:181], v[194:195], 0, s[90:91]
	s_barrier
	ds_read_b128 v[152:155], v187 offset:49152
	ds_read_b128 v[156:159], v187 offset:50176
	ds_read_b128 v[160:163], v187 offset:51200
	ds_read_b128 v[164:167], v187 offset:52224
	ds_read_b128 v[168:171], v187 offset:53248
	ds_read_b128 v[172:175], v187 offset:54272
	ds_read_b128 v[176:179], v187 offset:55296
	ds_read_b128 v[188:191], v187 offset:56320
	global_load_lds_dwordx4 v[180:181], off
	v_lshl_add_u64 v[180:181], v[196:197], 0, s[90:91]
	s_mov_b32 m0, s48
	s_nop 0
	global_load_lds_dwordx4 v[180:181], off
	s_barrier
; #define PG8_STAGE(bufoff, gbase, voff) do { _Pragma("unroll") for (int _i = 0; _i < 2; ++_i) \
;         __builtin_amdgcn_global_load_lds((const unsigned*)((const char*)(gbase) + (voff)[_i]), (LAS unsigned*)(lds + (bufoff) + ldsw + _i * 8192), 16, 0, 0); } while (0)
; #define PG8_MMA(ai, bj, At, Bt) do { __builtin_amdgcn_s_setprio(1); _Pragma("unroll") for (int m = 0; m < 4; ++m) _Pragma("unroll") for (int n = 0; n < 2; ++n) _Pragma("unroll") for (int k = 0; k < 2; ++k) \
;         acc[ai][bj][m][n] = __builtin_amdgcn_mfma_f32_16x16x32_bf16(Bt[n][k], At[m][k], acc[ai][bj][m][n], 0, 0, 0); __builtin_amdgcn_s_setprio(0); } while (0)
; #define PG8_WAIT_V(n) asm volatile("s_waitcnt vmcnt(" #n ")" ::: "memory")
; #define PG8_WAIT_L(n) asm volatile("s_waitcnt lgkmcnt(" #n ")" ::: "memory")
; template <class Epi, class SchedT>
; DI void gemm_phase(LAS unsigned char* lds, const Gemm g, const SchedT& S, const Epi& E) {
;     ...
;             PG8_BAR; PG8_WAIT_L(0); PG8_MMA(1, 0, At, B0); PG8_BAR; PG8_SCHED;
;             PG8_STAGE(PG8_SB(1, 1), b3 + hstepB, voffB);
;             PG8_WAIT_V(6); PG8_BAR; PG8_MMA(1, 1, At, B1); PG8_BAR;
;     DI void operator()(AccRef acc, const Unit& u, int wr, int wc, int fr, int fq) const {
; #pragma unroll
;         for (int n = 0; n < 2; ++n) {
;             const int cg_ = 128 * u.pn + 32 * wc + 8 * fq + 4 * n;
;             f32x4 o[2][4];
; #pragma unroll
;             for (int bj = 0; bj < 2; ++bj) {
;                 const f32x4 w0 = *(const f32x4*)(cw + bj * DFF + cg_), w1 = *(const f32x4*)(cw + (size_t)2 * DFF + bj * DFF + cg_),
;                             w2 = *(const f32x4*)(cw + (size_t)4 * DFF + bj * DFF + cg_), wb = *(const f32x4*)(cb + bj * DFF + cg_);
; #pragma unroll
;                 for (int ai = 0; ai < 2; ++ai) {
;                     const int tok0 = 252 * u.pm - 1 + 126 * wr + 64 * ai;
; #pragma unroll
;                     for (int m = 0; m < 4; ++m) {
;                         const int tok = tok0 + 16 * m + fr; const int msk = tok < ML ? 4095 : 255;
;                         const bool hu = (tok & msk) != 0, hd = ((tok + 1) & msk) != 0;
;                         f32x4 r = acc[ai][bj][m][n] * w1 + wb;
;                         f32x4 w0m, w2m;
; #pragma unroll
;                         for (int j = 0; j < 4; ++j) { w0m[j] = hu ? w0[j] : 0.f; w2m[j] = hd ? w2[j] : 0.f; }
	s_waitcnt lgkmcnt(0)
	s_setprio 1
	s_waitcnt lgkmcnt(0)
	v_mfma_f32_16x16x32_bf16 v[110:113], v[136:139], v[152:155], v[110:113]
	v_mfma_f32_16x16x32_bf16 v[46:49], v[144:147], v[152:155], v[46:49]
	v_mfma_f32_16x16x32_bf16 v[106:109], v[136:139], v[160:163], v[106:109]
	v_mfma_f32_16x16x32_bf16 v[42:45], v[144:147], v[160:163], v[42:45]
	v_mfma_f32_16x16x32_bf16 v[102:105], v[136:139], v[168:171], v[102:105]
	v_mfma_f32_16x16x32_bf16 v[38:41], v[144:147], v[168:171], v[38:41]
	v_mfma_f32_16x16x32_bf16 v[98:101], v[136:139], v[176:179], v[98:101]
	v_mfma_f32_16x16x32_bf16 v[34:37], v[144:147], v[176:179], v[34:37]
	v_mfma_f32_16x16x32_bf16 v[110:113], v[140:143], v[156:159], v[110:113]
	v_mfma_f32_16x16x32_bf16 v[46:49], v[148:151], v[156:159], v[46:49]
	v_mfma_f32_16x16x32_bf16 v[106:109], v[140:143], v[164:167], v[106:109]
	v_mfma_f32_16x16x32_bf16 v[42:45], v[148:151], v[164:167], v[42:45]
	v_mfma_f32_16x16x32_bf16 v[102:105], v[140:143], v[172:175], v[102:105]
	v_mfma_f32_16x16x32_bf16 v[38:41], v[148:151], v[172:175], v[38:41]
	v_mfma_f32_16x16x32_bf16 v[98:101], v[140:143], v[188:191], v[98:101]
	v_mfma_f32_16x16x32_bf16 v[34:37], v[148:151], v[188:191], v[34:37]
	s_setprio 0
	s_barrier
	s_add_u32 s6, s6, 0x80080
	s_addc_u32 s7, s7, 0
	s_add_i32 s8, s8, s76
	v_lshl_add_u64 v[136:137], s[6:7], 0, v[130:131]
	s_mov_b32 m0, s8
	s_nop 0
	global_load_lds_dwordx4 v[136:137], off
	v_lshl_add_u64 v[136:137], s[6:7], 0, v[134:135]
	s_add_i32 m0, s8, 0x2000
	s_nop 0
	global_load_lds_dwordx4 v[136:137], off
	s_waitcnt vmcnt(6)
	s_barrier
	s_setprio 1
	v_mfma_f32_16x16x32_bf16 v[78:81], v[202:205], v[152:155], v[78:81]
	v_mfma_f32_16x16x32_bf16 v[14:17], v[210:213], v[152:155], v[14:17]
	v_mfma_f32_16x16x32_bf16 v[74:77], v[202:205], v[160:163], v[74:77]
	v_mfma_f32_16x16x32_bf16 v[10:13], v[210:213], v[160:163], v[10:13]
	v_mfma_f32_16x16x32_bf16 v[70:73], v[202:205], v[168:171], v[70:73]
	v_mfma_f32_16x16x32_bf16 v[6:9], v[210:213], v[168:171], v[6:9]
	v_mfma_f32_16x16x32_bf16 v[66:69], v[202:205], v[176:179], v[66:69]
	v_mfma_f32_16x16x32_bf16 v[2:5], v[210:213], v[176:179], v[2:5]
	v_mfma_f32_16x16x32_bf16 v[78:81], v[206:209], v[156:159], v[78:81]
	v_mfma_f32_16x16x32_bf16 v[14:17], v[214:217], v[156:159], v[14:17]
	v_mfma_f32_16x16x32_bf16 v[74:77], v[206:209], v[164:167], v[74:77]
	v_mfma_f32_16x16x32_bf16 v[10:13], v[214:217], v[164:167], v[10:13]
	v_mfma_f32_16x16x32_bf16 v[70:73], v[206:209], v[172:175], v[70:73]
	v_mfma_f32_16x16x32_bf16 v[6:9], v[214:217], v[172:175], v[6:9]
	v_mfma_f32_16x16x32_bf16 v[66:69], v[206:209], v[188:191], v[66:69]
	v_mfma_f32_16x16x32_bf16 v[2:5], v[214:217], v[188:191], v[2:5]
	s_setprio 0
	s_add_i32 s14, s14, 2
	s_add_u32 s0, s0, 0x100
	s_addc_u32 s1, s1, 0
	s_add_u32 s12, s12, 0x100
	s_addc_u32 s13, s13, 0
	s_cmp_gt_u32 s14, 29
	s_barrier
	s_cbranch_scc0 .LBB0_1601
	v_mov_b32_e32 v205, v184
	s_mov_b32 s0, s65
	v_mov_b32_e32 v0, v185
	s_mov_b32 s1, s89
	s_lshl_b32 s4, s4, 7
	s_lshl_b32 s1, s1, 5
	s_add_i32 s1, s1, s4
	v_lshl_add_u32 v146, v0, 3, s1
	s_mul_i32 s1, s10, 0xfc
	s_mulk_i32 s0, 0x7e
	v_subrev_co_u32_e64 v206, s[4:5], 1, v205
	s_add_i32 s0, s0, s1
	v_ashrrev_i32_e32 v147, 31, v146
	v_add_u32_e32 v0, s0, v206
	v_lshlrev_b64 v[130:131], 2, v[146:147]
	v_readlane_b32 s0, v255, 0
	v_lshl_add_u64 v[150:151], s[62:63], 0, v[130:131]
	v_readlane_b32 s1, v255, 1
	v_lshl_add_u64 v[174:175], s[84:85], 0, v[130:131]
	v_lshl_add_u64 v[172:173], s[50:51], 0, v[130:131]
	v_lshl_add_u64 v[148:149], s[0:1], 0, v[130:131]
	global_load_dwordx4 v[134:137], v[150:151], off
	global_load_dwordx4 v[130:133], v[174:175], off
	global_load_dwordx4 v[138:141], v[172:173], off
	global_load_dwordx4 v[142:145], v[148:149], off
	s_mov_b64 s[98:99], 0x5000
	v_lshl_add_u64 v[178:179], v[150:151], 0, s[98:99]
	v_lshl_add_u64 v[180:181], v[174:175], 0, s[98:99]
	v_lshl_add_u64 v[182:183], v[172:173], 0, s[98:99]
	v_lshl_add_u64 v[194:195], v[148:149], 0, s[98:99]
	global_load_dwordx4 v[218:221], v[180:181], off offset:2048
	global_load_dwordx4 v[222:225], v[194:195], off offset:2048
	global_load_dwordx4 v[226:229], v[178:179], off offset:2048
	global_load_dwordx4 v[230:233], v[182:183], off offset:2048
	global_load_dwordx4 v[234:237], v[150:151], off offset:16
	global_load_dwordx4 v[238:241], v[174:175], off offset:16
	global_load_dwordx4 v[242:245], v[172:173], off offset:16
	global_load_dwordx4 v[246:249], v[148:149], off offset:16
	global_load_dwordx4 v[250:253], v[178:179], off offset:2064
	global_load_dwordx4 v[208:211], v[180:181], off offset:2064
	global_load_dwordx4 v[212:215], v[182:183], off offset:2064
	global_load_dwordx4 v[196:199], v[194:195], off offset:2064
	v_cmp_gt_i32_e64 s[0:1], s72, v0
	v_mov_b32_e32 v176, 0xff
	v_mov_b32_e32 v177, 0xfff
	v_cndmask_b32_e64 v152, v176, v177, s[0:1]
	v_and_b32_e32 v153, v152, v0
	v_cmp_eq_u32_e64 s[6:7], 0, v153
	v_add_u32_e32 v153, 1, v0
	v_and_b32_e32 v152, v152, v153
	v_add_u32_e32 v188, 16, v0
	v_cmp_eq_u32_e64 s[8:9], 0, v152
	v_cmp_gt_i32_e64 s[0:1], s72, v188
	v_cndmask_b32_e64 v167, v126, v122, s[4:5]
	v_cmp_eq_u32_e32 vcc, 15, v205
	v_add_u32_e32 v189, 32, v0
	v_cndmask_b32_e64 v166, v127, v123, s[4:5]
	v_cndmask_b32_e64 v164, v129, v125, s[4:5]
	v_add_u32_e32 v191, 48, v0
	v_cndmask_b32_e64 v165, v128, v124, s[4:5]
	v_cndmask_b32_e64 v170, v123, v119, s[4:5]
	v_cndmask_b32_e64 v171, v122, v118, s[4:5]
	v_cndmask_b32_e64 v168, v125, v121, s[4:5]
	v_add_u32_e32 v202, 64, v0
	v_cndmask_b32_e64 v169, v124, v120, s[4:5]
	v_add_u32_e32 v204, 0x50, v0
	v_add_u32_e32 v203, 0x60, v0
	v_add_u32_e32 v190, 0x70, v0
	s_movk_i32 s33, 0x5000
	v_readlane_b32 s44, v254, 63
	s_waitcnt vmcnt(12)
;     DI void operator()(AccRef acc, const Unit& u, int wr, int wc, int fr, int fq) const {
;     ...
;             for (int bj = 0; bj < 2; ++bj) {
;                 const f32x4 w0 = *(const f32x4*)(cw + bj * DFF + cg_), w1 = *(const f32x4*)(cw + (size_t)2 * DFF + bj * DFF + cg_),
;                             w2 = *(const f32x4*)(cw + (size_t)4 * DFF + bj * DFF + cg_), wb = *(const f32x4*)(cb + bj * DFF + cg_);
; #pragma unroll
;                 for (int ai = 0; ai < 2; ++ai) {
;                     const int tok0 = 252 * u.pm - 1 + 126 * wr + 64 * ai;
; #pragma unroll
;                     for (int m = 0; m < 4; ++m) {
;                         const int tok = tok0 + 16 * m + fr; const int msk = tok < ML ? 4095 : 255;
;                         const bool hu = (tok & msk) != 0, hd = ((tok + 1) & msk) != 0;
;                         f32x4 r = acc[ai][bj][m][n] * w1 + wb;
;                         f32x4 w0m, w2m;
; #pragma unroll
;                         for (int j = 0; j < 4; ++j) { w0m[j] = hu ? w0[j] : 0.f; w2m[j] = hd ? w2[j] : 0.f; }
; #pragma unroll
;                         for (int j = 0; j < 4; ++j) {
;                             const float su = ((m > 0 || ai == 1) && fr == 15) ? (m > 0 ? acc[ai][bj][(m + 3) & 3][n][j] : acc[0][bj][3][n][j]) : acc[ai][bj][m][n][j];
;                             const float sd = ((m < 3 || ai == 0) && fr == 0) ? (m < 3 ? acc[ai][bj][(m + 1) & 3][n][j] : acc[1][bj][0][n][j]) : acc[ai][bj][m][n][j];
;                             float rj = r[j];
;                             asm("s_nop 1\n\tv_fmac_f32_dpp %0, %1, %2 row_ror:1 row_mask:0xf bank_mask:0xf" : "+v"(rj) : "v"(su), "v"(w0m[j]));
;                             asm("s_nop 1\n\tv_fmac_f32_dpp %0, %1, %2 row_ror:15 row_mask:0xf bank_mask:0xf" : "+v"(rj) : "v"(sd), "v"(w2m[j]));
;                             r[j] = rj; }
	v_cndmask_b32_e64 v156, v134, 0, s[6:7]
	v_cndmask_b32_e64 v158, v135, 0, s[6:7]
	v_cndmask_b32_e64 v157, v138, 0, s[8:9]
	v_pk_fma_f32 v[154:155], v[126:127], v[130:131], v[142:143]
	v_cndmask_b32_e64 v159, v139, 0, s[8:9]
	s_nop 1
	v_fmac_f32_dpp v154, v126, v156 row_ror:1 row_mask:0xf bank_mask:0xf
	v_cndmask_b32_e64 v156, v176, v177, s[0:1]
	s_nop 1
	v_fmac_f32_dpp v154, v167, v157 row_ror:15 row_mask:0xf bank_mask:0xf
	v_and_b32_e32 v157, v156, v188
	s_nop 1
	v_fmac_f32_dpp v155, v127, v158 row_ror:1 row_mask:0xf bank_mask:0xf
	v_cmp_eq_u32_e64 s[10:11], 0, v157
	v_add_u32_e32 v157, 17, v0
	v_cndmask_b32_e64 v160, v136, 0, s[6:7]
	v_pk_fma_f32 v[152:153], v[128:129], v[132:133], v[144:145]
	s_nop 1
	v_fmac_f32_dpp v155, v166, v159 row_ror:15 row_mask:0xf bank_mask:0xf
	v_and_b32_e32 v156, v156, v157
	v_pk_fma_f32 v[158:159], v[122:123], v[130:131], v[142:143]
	v_cndmask_b32_e32 v126, v122, v126, vcc
	v_cmp_gt_i32_e64 s[0:1], s72, v189
	v_cndmask_b32_e64 v162, v137, 0, s[6:7]
	v_cndmask_b32_e64 v163, v141, 0, s[8:9]
	s_nop 1
	v_fmac_f32_dpp v152, v128, v160 row_ror:1 row_mask:0xf bank_mask:0xf
	s_nop 1
	v_fmac_f32_dpp v153, v129, v162 row_ror:1 row_mask:0xf bank_mask:0xf
	v_cmp_eq_u32_e64 s[12:13], 0, v156
	v_cndmask_b32_e64 v160, v134, 0, s[10:11]
	v_cndmask_b32_e32 v127, v123, v127, vcc
	s_nop 1
	v_fmac_f32_dpp v158, v126, v160 row_ror:1 row_mask:0xf bank_mask:0xf
	v_cndmask_b32_e64 v126, v176, v177, s[0:1]
	s_nop 1
	v_fmac_f32_dpp v153, v164, v163 row_ror:15 row_mask:0xf bank_mask:0xf
	v_cndmask_b32_e64 v162, v135, 0, s[10:11]
	v_cndmask_b32_e64 v163, v139, 0, s[12:13]
	s_nop 1
	v_fmac_f32_dpp v159, v127, v162 row_ror:1 row_mask:0xf bank_mask:0xf
	v_and_b32_e32 v127, v126, v189
	v_pk_fma_f32 v[156:157], v[124:125], v[132:133], v[144:145]
	v_cndmask_b32_e32 v128, v124, v128, vcc
	s_nop 1
	v_fmac_f32_dpp v159, v170, v163 row_ror:15 row_mask:0xf bank_mask:0xf
	v_cmp_eq_u32_e64 s[14:15], 0, v127
	v_add_u32_e32 v127, 33, v0
	v_pk_fma_f32 v[162:163], v[118:119], v[130:131], v[142:143]
	v_cndmask_b32_e32 v122, v118, v122, vcc
	v_cmp_gt_i32_e64 s[0:1], s72, v191
	v_cndmask_b32_e64 v164, v136, 0, s[10:11]
	s_nop 1
	v_fmac_f32_dpp v156, v128, v164 row_ror:1 row_mask:0xf bank_mask:0xf
	v_and_b32_e32 v126, v126, v127
	v_cndmask_b32_e64 v128, v134, 0, s[14:15]
	v_cndmask_b32_e32 v123, v119, v123, vcc
	s_nop 1
	v_fmac_f32_dpp v162, v122, v128 row_ror:1 row_mask:0xf bank_mask:0xf
	v_cndmask_b32_e64 v122, v176, v177, s[0:1]
	v_cndmask_b32_e64 v166, v137, 0, s[10:11]
	v_cndmask_b32_e64 v167, v141, 0, s[12:13]
	v_cndmask_b32_e32 v129, v125, v129, vcc
	s_nop 1
	v_fmac_f32_dpp v157, v129, v166 row_ror:1 row_mask:0xf bank_mask:0xf
	v_cmp_eq_u32_e64 s[16:17], 0, v126
	v_cndmask_b32_e64 v160, v135, 0, s[14:15]
	v_pk_fma_f32 v[126:127], v[120:121], v[132:133], v[144:145]
	s_nop 1
	v_fmac_f32_dpp v163, v123, v160 row_ror:1 row_mask:0xf bank_mask:0xf
	v_and_b32_e32 v123, v122, v191
	v_cndmask_b32_e64 v161, v140, 0, s[8:9]
	s_nop 1
	v_fmac_f32_dpp v157, v168, v167 row_ror:15 row_mask:0xf bank_mask:0xf
	v_cndmask_b32_e64 v166, v137, 0, s[14:15]
	v_cndmask_b32_e64 v167, v141, 0, s[16:17]
	v_cndmask_b32_e32 v125, v121, v125, vcc
	s_nop 1
	v_fmac_f32_dpp v127, v125, v166 row_ror:1 row_mask:0xf bank_mask:0xf
	v_cmp_eq_u32_e64 s[18:19], 0, v123
	v_add_u32_e32 v123, 49, v0
	s_nop 1
	v_fmac_f32_dpp v152, v165, v161 row_ror:15 row_mask:0xf bank_mask:0xf
	v_cndmask_b32_e64 v161, v138, 0, s[12:13]
	s_nop 1
	v_fmac_f32_dpp v158, v171, v161 row_ror:15 row_mask:0xf bank_mask:0xf
	v_cndmask_b32_e64 v168, v121, v117, s[4:5]
	v_cndmask_b32_e64 v171, v118, v114, s[4:5]
	s_nop 1
	v_fmac_f32_dpp v127, v168, v167 row_ror:15 row_mask:0xf bank_mask:0xf
	v_and_b32_e32 v122, v122, v123
	v_pk_fma_f32 v[166:167], v[114:115], v[130:131], v[142:143]
	v_cndmask_b32_e32 v118, v114, v118, vcc
	v_cmp_gt_i32_e64 s[0:1], s72, v202
	v_cndmask_b32_e64 v129, v138, 0, s[16:17]
	v_cndmask_b32_e32 v124, v120, v124, vcc
	v_cndmask_b32_e64 v170, v119, v115, s[4:5]
	v_cmp_eq_u32_e64 s[20:21], 0, v122
	v_cndmask_b32_e64 v122, v134, 0, s[18:19]
	v_cndmask_b32_e32 v119, v115, v119, vcc
	s_nop 1
	v_fmac_f32_dpp v166, v118, v122 row_ror:1 row_mask:0xf bank_mask:0xf
	v_cndmask_b32_e64 v118, v176, v177, s[0:1]
	v_cndmask_b32_e64 v165, v140, 0, s[12:13]
	s_nop 1
	v_fmac_f32_dpp v156, v169, v165 row_ror:15 row_mask:0xf bank_mask:0xf
	v_cndmask_b32_e64 v164, v136, 0, s[14:15]
	v_cndmask_b32_e64 v169, v120, v116, s[4:5]
	s_nop 1
	v_fmac_f32_dpp v162, v171, v129 row_ror:15 row_mask:0xf bank_mask:0xf
	s_nop 1
	v_fmac_f32_dpp v126, v124, v164 row_ror:1 row_mask:0xf bank_mask:0xf
	v_cndmask_b32_e64 v124, v135, 0, s[18:19]
	v_pk_fma_f32 v[128:129], v[116:117], v[132:133], v[144:145]
	s_nop 1
	v_fmac_f32_dpp v167, v119, v124 row_ror:1 row_mask:0xf bank_mask:0xf
	v_and_b32_e32 v119, v118, v202
	v_cndmask_b32_e64 v161, v139, 0, s[16:17]
	v_cndmask_b32_e64 v165, v140, 0, s[16:17]
	s_nop 1
	v_fmac_f32_dpp v126, v169, v165 row_ror:15 row_mask:0xf bank_mask:0xf
	v_cndmask_b32_e64 v160, v136, 0, s[18:19]
	v_cndmask_b32_e64 v164, v137, 0, s[18:19]
	v_cndmask_b32_e32 v121, v117, v121, vcc
	v_cndmask_b32_e32 v120, v116, v120, vcc
	v_cndmask_b32_e64 v168, v117, v113, s[4:5]
	v_cndmask_b32_e64 v169, v116, v112, s[4:5]
	s_nop 1
	v_fmac_f32_dpp v128, v120, v160 row_ror:1 row_mask:0xf bank_mask:0xf
	s_nop 1
	v_fmac_f32_dpp v129, v121, v164 row_ror:1 row_mask:0xf bank_mask:0xf
	v_cmp_eq_u32_e64 s[22:23], 0, v119
	v_add_u32_e32 v119, 0x41, v0
	s_nop 1
	v_fmac_f32_dpp v163, v170, v161 row_ror:15 row_mask:0xf bank_mask:0xf
	v_cndmask_b32_e64 v161, v140, 0, s[20:21]
	v_cndmask_b32_e64 v165, v141, 0, s[20:21]
	v_cndmask_b32_e64 v171, v114, v110, s[4:5]
;     DI void operator()(AccRef acc, const Unit& u, int wr, int wc, int fr, int fq) const {
;     ...
;             for (int bj = 0; bj < 2; ++bj) {
;                 const f32x4 w0 = *(const f32x4*)(cw + bj * DFF + cg_), w1 = *(const f32x4*)(cw + (size_t)2 * DFF + bj * DFF + cg_),
;                             w2 = *(const f32x4*)(cw + (size_t)4 * DFF + bj * DFF + cg_), wb = *(const f32x4*)(cb + bj * DFF + cg_);
; #pragma unroll
;                 for (int ai = 0; ai < 2; ++ai) {
;                     const int tok0 = 252 * u.pm - 1 + 126 * wr + 64 * ai;
; #pragma unroll
;                     for (int m = 0; m < 4; ++m) {
;                         const int tok = tok0 + 16 * m + fr; const int msk = tok < ML ? 4095 : 255;
;                         const bool hu = (tok & msk) != 0, hd = ((tok + 1) & msk) != 0;
;                         f32x4 r = acc[ai][bj][m][n] * w1 + wb;
;                         f32x4 w0m, w2m;
; #pragma unroll
;                         for (int j = 0; j < 4; ++j) { w0m[j] = hu ? w0[j] : 0.f; w2m[j] = hd ? w2[j] : 0.f; }
; #pragma unroll
;                         for (int j = 0; j < 4; ++j) {
;                             const float su = ((m > 0 || ai == 1) && fr == 15) ? (m > 0 ? acc[ai][bj][(m + 3) & 3][n][j] : acc[0][bj][3][n][j]) : acc[ai][bj][m][n][j];
;                             const float sd = ((m < 3 || ai == 0) && fr == 0) ? (m < 3 ? acc[ai][bj][(m + 1) & 3][n][j] : acc[1][bj][0][n][j]) : acc[ai][bj][m][n][j];
;                             float rj = r[j];
;                             asm("s_nop 1\n\tv_fmac_f32_dpp %0, %1, %2 row_ror:1 row_mask:0xf bank_mask:0xf" : "+v"(rj) : "v"(su), "v"(w0m[j]));
;                             asm("s_nop 1\n\tv_fmac_f32_dpp %0, %1, %2 row_ror:15 row_mask:0xf bank_mask:0xf" : "+v"(rj) : "v"(sd), "v"(w2m[j]));
;                             r[j] = rj; }
	s_nop 1
	v_fmac_f32_dpp v128, v169, v161 row_ror:15 row_mask:0xf bank_mask:0xf
	s_nop 1
	v_fmac_f32_dpp v129, v168, v165 row_ror:15 row_mask:0xf bank_mask:0xf
	v_and_b32_e32 v118, v118, v119
	v_pk_fma_f32 v[168:169], v[110:111], v[130:131], v[142:143]
	v_cndmask_b32_e32 v114, v110, v114, vcc
	v_cmp_gt_i32_e64 s[0:1], s72, v204
	v_cndmask_b32_e64 v170, v115, v111, s[4:5]
	v_cmp_eq_u32_e64 s[24:25], 0, v118
	v_cndmask_b32_e64 v118, v134, 0, s[22:23]
	v_cndmask_b32_e32 v115, v111, v115, vcc
	s_nop 1
	v_fmac_f32_dpp v168, v114, v118 row_ror:1 row_mask:0xf bank_mask:0xf
	v_cndmask_b32_e64 v114, v176, v177, s[0:1]
	v_cndmask_b32_e64 v120, v135, 0, s[22:23]
	s_nop 1
	v_fmac_f32_dpp v169, v115, v120 row_ror:1 row_mask:0xf bank_mask:0xf
	v_and_b32_e32 v115, v114, v204
	v_cndmask_b32_e64 v123, v138, 0, s[20:21]
	v_cndmask_b32_e64 v125, v139, 0, s[20:21]
	s_nop 1
	v_fmac_f32_dpp v166, v171, v123 row_ror:15 row_mask:0xf bank_mask:0xf
	s_nop 1
	v_fmac_f32_dpp v167, v170, v125 row_ror:15 row_mask:0xf bank_mask:0xf
	v_cndmask_b32_e64 v170, v111, v107, s[4:5]
	v_cndmask_b32_e64 v171, v110, v106, s[4:5]
	v_cmp_eq_u32_e64 s[26:27], 0, v115
	v_add_u32_e32 v115, 0x51, v0
	v_cndmask_b32_e64 v119, v138, 0, s[24:25]
	v_cndmask_b32_e64 v121, v139, 0, s[24:25]
	s_nop 1
	v_fmac_f32_dpp v168, v171, v119 row_ror:15 row_mask:0xf bank_mask:0xf
	s_nop 1
	v_fmac_f32_dpp v169, v170, v121 row_ror:15 row_mask:0xf bank_mask:0xf
	v_and_b32_e32 v114, v114, v115
	v_pk_fma_f32 v[170:171], v[106:107], v[130:131], v[142:143]
	v_cndmask_b32_e32 v110, v106, v110, vcc
	v_cmp_gt_i32_e64 s[0:1], s72, v203
	v_pk_fma_f32 v[160:161], v[112:113], v[132:133], v[144:145]
	v_cndmask_b32_e32 v116, v112, v116, vcc
	v_cmp_eq_u32_e64 s[30:31], 0, v114
	v_cndmask_b32_e64 v114, v134, 0, s[26:27]
	v_cndmask_b32_e32 v111, v107, v111, vcc
	s_nop 1
	v_fmac_f32_dpp v170, v110, v114 row_ror:1 row_mask:0xf bank_mask:0xf
	v_cndmask_b32_e64 v110, v176, v177, s[0:1]
	v_cndmask_b32_e64 v122, v136, 0, s[22:23]
	v_cndmask_b32_e64 v124, v137, 0, s[22:23]
	v_cndmask_b32_e64 v125, v141, 0, s[24:25]
	v_cndmask_b32_e32 v117, v113, v117, vcc
	s_nop 1
	v_fmac_f32_dpp v160, v116, v122 row_ror:1 row_mask:0xf bank_mask:0xf
	s_nop 1
	v_fmac_f32_dpp v161, v117, v124 row_ror:1 row_mask:0xf bank_mask:0xf
	v_cndmask_b32_e64 v116, v135, 0, s[26:27]
	s_nop 1
	v_fmac_f32_dpp v171, v111, v116 row_ror:1 row_mask:0xf bank_mask:0xf
	v_and_b32_e32 v111, v110, v203
	v_cndmask_b32_e64 v164, v113, v109, s[4:5]
	s_nop 1
	v_fmac_f32_dpp v161, v164, v125 row_ror:15 row_mask:0xf bank_mask:0xf
	v_cndmask_b32_e64 v124, v107, v103, s[4:5]
	v_cndmask_b32_e64 v125, v106, v102, s[4:5]
	v_cmp_eq_u32_e64 s[36:37], 0, v111
	v_add_u32_e32 v111, 0x61, v0
	v_cndmask_b32_e64 v165, v112, v108, s[4:5]
	v_cndmask_b32_e64 v115, v138, 0, s[30:31]
	v_cndmask_b32_e64 v117, v139, 0, s[30:31]
	s_nop 1
	v_fmac_f32_dpp v170, v125, v115 row_ror:15 row_mask:0xf bank_mask:0xf
	s_nop 1
	v_fmac_f32_dpp v171, v124, v117 row_ror:15 row_mask:0xf bank_mask:0xf
	v_and_b32_e32 v110, v110, v111
	v_pk_fma_f32 v[124:125], v[102:103], v[130:131], v[142:143]
	v_cndmask_b32_e32 v106, v102, v106, vcc
	v_cmp_gt_i32_e64 s[0:1], s72, v190
	v_cndmask_b32_e64 v123, v140, 0, s[24:25]
	s_nop 1
	v_fmac_f32_dpp v160, v165, v123 row_ror:15 row_mask:0xf bank_mask:0xf
	v_pk_fma_f32 v[164:165], v[108:109], v[132:133], v[144:145]
	v_cndmask_b32_e32 v112, v108, v112, vcc
	v_cmp_eq_u32_e64 s[38:39], 0, v110
	v_cndmask_b32_e64 v110, v134, 0, s[36:37]
	v_cndmask_b32_e32 v107, v103, v107, vcc
	s_nop 1
	v_fmac_f32_dpp v124, v106, v110 row_ror:1 row_mask:0xf bank_mask:0xf
	v_cndmask_b32_e64 v106, v176, v177, s[0:1]
	v_cndmask_b32_e64 v118, v136, 0, s[26:27]
	v_cndmask_b32_e64 v120, v137, 0, s[26:27]
	v_cndmask_b32_e64 v121, v141, 0, s[30:31]
	v_cndmask_b32_e32 v113, v109, v113, vcc
	v_cndmask_b32_e64 v122, v109, v105, s[4:5]
	v_cndmask_b32_e64 v123, v108, v104, s[4:5]
	s_nop 1
	v_fmac_f32_dpp v164, v112, v118 row_ror:1 row_mask:0xf bank_mask:0xf
	s_nop 1
	v_fmac_f32_dpp v165, v113, v120 row_ror:1 row_mask:0xf bank_mask:0xf
	v_cndmask_b32_e64 v112, v135, 0, s[36:37]
	s_nop 1
	v_fmac_f32_dpp v125, v107, v112 row_ror:1 row_mask:0xf bank_mask:0xf
	v_and_b32_e32 v107, v106, v190
	v_cndmask_b32_e64 v119, v140, 0, s[30:31]
	s_nop 1
	v_fmac_f32_dpp v164, v123, v119 row_ror:15 row_mask:0xf bank_mask:0xf
	s_nop 1
	v_fmac_f32_dpp v165, v122, v121 row_ror:15 row_mask:0xf bank_mask:0xf
	v_cndmask_b32_e64 v116, v137, 0, s[36:37]
	v_pk_fma_f32 v[122:123], v[104:105], v[132:133], v[144:145]
	v_cndmask_b32_e64 v120, v103, v99, s[4:5]
	v_cndmask_b32_e64 v121, v102, v98, s[4:5]
	v_cmp_eq_u32_e64 s[28:29], 0, v107
	v_add_u32_e32 v107, 0x71, v0
	v_cndmask_b32_e64 v111, v138, 0, s[38:39]
	v_cndmask_b32_e64 v113, v139, 0, s[38:39]
	v_cndmask_b32_e64 v117, v141, 0, s[38:39]
	v_cndmask_b32_e32 v109, v105, v109, vcc
	s_nop 1
	v_fmac_f32_dpp v124, v121, v111 row_ror:15 row_mask:0xf bank_mask:0xf
	s_nop 1
	v_fmac_f32_dpp v125, v120, v113 row_ror:15 row_mask:0xf bank_mask:0xf
	s_nop 1
	v_fmac_f32_dpp v123, v109, v116 row_ror:1 row_mask:0xf bank_mask:0xf
	v_and_b32_e32 v106, v106, v107
	v_pk_fma_f32 v[120:121], v[98:99], v[130:131], v[142:143]
	v_add_co_u32_e64 v116, s[0:1], s33, v150
	v_cndmask_b32_e32 v108, v104, v108, vcc
	v_cndmask_b32_e64 v118, v105, v101, s[4:5]
	s_nop 1
	v_fmac_f32_dpp v123, v118, v117 row_ror:15 row_mask:0xf bank_mask:0xf
	v_cmp_eq_u32_e64 s[34:35], 0, v106
	v_cndmask_b32_e64 v106, v134, 0, s[28:29]
	v_cndmask_b32_e32 v102, v98, v102, vcc
	s_nop 1
	v_fmac_f32_dpp v120, v102, v106 row_ror:1 row_mask:0xf bank_mask:0xf
	v_addc_co_u32_e64 v117, s[0:1], 0, v151, s[0:1]
	v_cndmask_b32_e64 v114, v136, 0, s[36:37]
;     DI void operator()(AccRef acc, const Unit& u, int wr, int wc, int fr, int fq) const {
;     ...
;             for (int bj = 0; bj < 2; ++bj) {
;                 const f32x4 w0 = *(const f32x4*)(cw + bj * DFF + cg_), w1 = *(const f32x4*)(cw + (size_t)2 * DFF + bj * DFF + cg_),
;                             w2 = *(const f32x4*)(cw + (size_t)4 * DFF + bj * DFF + cg_), wb = *(const f32x4*)(cb + bj * DFF + cg_);
; #pragma unroll
;                 for (int ai = 0; ai < 2; ++ai) {
;                     const int tok0 = 252 * u.pm - 1 + 126 * wr + 64 * ai;
; #pragma unroll
;                     for (int m = 0; m < 4; ++m) {
;                         const int tok = tok0 + 16 * m + fr; const int msk = tok < ML ? 4095 : 255;
;                         const bool hu = (tok & msk) != 0, hd = ((tok + 1) & msk) != 0;
;                         f32x4 r = acc[ai][bj][m][n] * w1 + wb;
;                         f32x4 w0m, w2m;
; #pragma unroll
;                         for (int j = 0; j < 4; ++j) { w0m[j] = hu ? w0[j] : 0.f; w2m[j] = hd ? w2[j] : 0.f; }
; #pragma unroll
;                         for (int j = 0; j < 4; ++j) {
;                             const float su = ((m > 0 || ai == 1) && fr == 15) ? (m > 0 ? acc[ai][bj][(m + 3) & 3][n][j] : acc[0][bj][3][n][j]) : acc[ai][bj][m][n][j];
;                             const float sd = ((m < 3 || ai == 0) && fr == 0) ? (m < 3 ? acc[ai][bj][(m + 1) & 3][n][j] : acc[1][bj][0][n][j]) : acc[ai][bj][m][n][j];
;                             float rj = r[j];
;                             asm("s_nop 1\n\tv_fmac_f32_dpp %0, %1, %2 row_ror:1 row_mask:0xf bank_mask:0xf" : "+v"(rj) : "v"(su), "v"(w0m[j]));
;                             asm("s_nop 1\n\tv_fmac_f32_dpp %0, %1, %2 row_ror:15 row_mask:0xf bank_mask:0xf" : "+v"(rj) : "v"(sd), "v"(w2m[j]));
;                             r[j] = rj; }
	s_nop 1
	v_fmac_f32_dpp v122, v108, v114 row_ror:1 row_mask:0xf bank_mask:0xf
	v_cndmask_b32_e64 v107, v138, 0, s[34:35]
	v_cndmask_b32_e64 v108, v135, 0, s[28:29]
	v_cndmask_b32_e32 v103, v99, v103, vcc
	s_nop 1
	v_fmac_f32_dpp v120, v98, v107 row_ror:15 row_mask:0xf bank_mask:0xf
	s_nop 1
	v_fmac_f32_dpp v121, v103, v108 row_ror:1 row_mask:0xf bank_mask:0xf
	v_add_co_u32_e64 v98, s[0:1], s33, v174
	v_cndmask_b32_e64 v109, v139, 0, s[34:35]
	s_nop 1
	v_fmac_f32_dpp v121, v99, v109 row_ror:15 row_mask:0xf bank_mask:0xf
	s_nop 0
	v_addc_co_u32_e64 v99, s[0:1], 0, v175, s[0:1]
	v_add_co_u32_e64 v106, s[0:1], s33, v172
	v_cndmask_b32_e64 v119, v104, v100, s[4:5]
	s_nop 0
	v_addc_co_u32_e64 v107, s[0:1], 0, v173, s[0:1]
	v_cndmask_b32_e64 v115, v140, 0, s[38:39]
	s_nop 1
	v_fmac_f32_dpp v122, v119, v115 row_ror:15 row_mask:0xf bank_mask:0xf
	v_pk_fma_f32 v[118:119], v[100:101], v[132:133], v[144:145]
	v_add_co_u32_e64 v114, s[0:1], s33, v148
	v_cndmask_b32_e64 v110, v136, 0, s[28:29]
	v_cndmask_b32_e64 v111, v140, 0, s[34:35]
	v_cndmask_b32_e64 v112, v137, 0, s[28:29]
	v_cndmask_b32_e64 v113, v141, 0, s[34:35]
	v_cndmask_b32_e32 v105, v101, v105, vcc
	v_cndmask_b32_e32 v104, v100, v104, vcc
	s_nop 1
	v_fmac_f32_dpp v118, v104, v110 row_ror:1 row_mask:0xf bank_mask:0xf
	s_nop 1
	v_fmac_f32_dpp v119, v105, v112 row_ror:1 row_mask:0xf bank_mask:0xf
	v_addc_co_u32_e64 v115, s[0:1], 0, v149, s[0:1]
	s_nop 1
	v_fmac_f32_dpp v118, v100, v111 row_ror:15 row_mask:0xf bank_mask:0xf
	s_nop 1
	v_fmac_f32_dpp v119, v101, v113 row_ror:15 row_mask:0xf bank_mask:0xf
	v_cndmask_b32_e64 v142, v97, v93, s[4:5]
	v_cndmask_b32_e64 v143, v96, v92, s[4:5]
	v_cndmask_b32_e64 v144, v95, v91, s[4:5]
	v_cndmask_b32_e64 v145, v94, v90, s[4:5]
	v_cndmask_b32_e64 v172, v93, v89, s[4:5]
	v_cndmask_b32_e64 v173, v92, v88, s[4:5]
	v_cndmask_b32_e64 v174, v91, v87, s[4:5]
	v_cndmask_b32_e64 v175, v90, v86, s[4:5]
	v_cmp_gt_u32_e64 s[0:1], s46, v206
	v_cmp_gt_i32_e64 s[42:43], s44, v0
	s_and_b64 s[54:55], s[0:1], s[42:43]
	s_waitcnt vmcnt(0)
	v_pk_fma_f32 v[134:135], v[94:95], v[218:219], v[222:223]
	v_cndmask_b32_e64 v130, v226, 0, s[6:7]
	v_cndmask_b32_e64 v132, v227, 0, s[6:7]
	v_cndmask_b32_e64 v131, v230, 0, s[8:9]
	v_cndmask_b32_e64 v133, v231, 0, s[8:9]
	v_pk_fma_f32 v[136:137], v[96:97], v[220:221], v[224:225]
	s_nop 1
	v_fmac_f32_dpp v134, v94, v130 row_ror:1 row_mask:0xf bank_mask:0xf
	s_nop 1
	v_fmac_f32_dpp v135, v95, v132 row_ror:1 row_mask:0xf bank_mask:0xf
	v_cndmask_b32_e64 v138, v228, 0, s[6:7]
	v_cndmask_b32_e64 v140, v229, 0, s[6:7]
	s_nop 1
	v_fmac_f32_dpp v134, v145, v131 row_ror:15 row_mask:0xf bank_mask:0xf
	s_nop 1
	v_fmac_f32_dpp v135, v144, v133 row_ror:15 row_mask:0xf bank_mask:0xf
	s_nop 1
	v_fmac_f32_dpp v136, v96, v138 row_ror:1 row_mask:0xf bank_mask:0xf
	s_nop 1
	v_fmac_f32_dpp v137, v97, v140 row_ror:1 row_mask:0xf bank_mask:0xf
	v_pk_fma_f32 v[132:133], v[92:93], v[220:221], v[224:225]
	v_pk_fma_f32 v[130:131], v[90:91], v[218:219], v[222:223]
	v_cndmask_b32_e32 v97, v93, v97, vcc
	v_cndmask_b32_e32 v96, v92, v96, vcc
	v_cndmask_b32_e32 v95, v91, v95, vcc
	v_cndmask_b32_e32 v94, v90, v94, vcc
	v_cndmask_b32_e64 v139, v232, 0, s[8:9]
	v_cndmask_b32_e64 v141, v233, 0, s[8:9]
	s_nop 1
	v_fmac_f32_dpp v137, v142, v141 row_ror:15 row_mask:0xf bank_mask:0xf
	v_cndmask_b32_e64 v138, v226, 0, s[10:11]
	v_cndmask_b32_e64 v140, v227, 0, s[10:11]
	v_cndmask_b32_e64 v142, v228, 0, s[10:11]
	v_cndmask_b32_e64 v144, v229, 0, s[10:11]
	s_nop 1
	v_fmac_f32_dpp v130, v94, v138 row_ror:1 row_mask:0xf bank_mask:0xf
	s_nop 1
	v_fmac_f32_dpp v131, v95, v140 row_ror:1 row_mask:0xf bank_mask:0xf
	s_nop 1
	v_fmac_f32_dpp v132, v96, v142 row_ror:1 row_mask:0xf bank_mask:0xf
	s_nop 1
	v_fmac_f32_dpp v133, v97, v144 row_ror:1 row_mask:0xf bank_mask:0xf
	v_pk_fma_f32 v[96:97], v[88:89], v[220:221], v[224:225]
	v_pk_fma_f32 v[94:95], v[86:87], v[218:219], v[222:223]
	v_cndmask_b32_e32 v93, v89, v93, vcc
	v_cndmask_b32_e32 v92, v88, v92, vcc
	v_cndmask_b32_e32 v91, v87, v91, vcc
	v_cndmask_b32_e32 v90, v86, v90, vcc
	s_nop 1
	v_fmac_f32_dpp v136, v143, v139 row_ror:15 row_mask:0xf bank_mask:0xf
	v_cndmask_b32_e64 v139, v230, 0, s[12:13]
	v_cndmask_b32_e64 v141, v231, 0, s[12:13]
	v_cndmask_b32_e64 v143, v232, 0, s[12:13]
	v_cndmask_b32_e64 v145, v233, 0, s[12:13]
	s_nop 1
	v_fmac_f32_dpp v130, v175, v139 row_ror:15 row_mask:0xf bank_mask:0xf
	s_nop 1
	v_fmac_f32_dpp v131, v174, v141 row_ror:15 row_mask:0xf bank_mask:0xf
	s_nop 1
	v_fmac_f32_dpp v132, v173, v143 row_ror:15 row_mask:0xf bank_mask:0xf
	s_nop 1
	v_fmac_f32_dpp v133, v172, v145 row_ror:15 row_mask:0xf bank_mask:0xf
	v_cndmask_b32_e64 v138, v226, 0, s[14:15]
	v_cndmask_b32_e64 v140, v227, 0, s[14:15]
	v_cndmask_b32_e64 v142, v228, 0, s[14:15]
	v_cndmask_b32_e64 v144, v229, 0, s[14:15]
	v_cndmask_b32_e64 v172, v89, v85, s[4:5]
	v_cndmask_b32_e64 v173, v88, v84, s[4:5]
	v_cndmask_b32_e64 v174, v87, v83, s[4:5]
	v_cndmask_b32_e64 v175, v86, v82, s[4:5]
	s_nop 1
	v_fmac_f32_dpp v94, v90, v138 row_ror:1 row_mask:0xf bank_mask:0xf
	s_nop 1
	v_fmac_f32_dpp v95, v91, v140 row_ror:1 row_mask:0xf bank_mask:0xf
	s_nop 1
	v_fmac_f32_dpp v96, v92, v142 row_ror:1 row_mask:0xf bank_mask:0xf
	s_nop 1
	v_fmac_f32_dpp v97, v93, v144 row_ror:1 row_mask:0xf bank_mask:0xf
	v_pk_fma_f32 v[92:93], v[84:85], v[220:221], v[224:225]
	v_pk_fma_f32 v[90:91], v[82:83], v[218:219], v[222:223]
	v_cndmask_b32_e32 v89, v85, v89, vcc
	v_cndmask_b32_e32 v88, v84, v88, vcc
	v_cndmask_b32_e32 v87, v83, v87, vcc
	v_cndmask_b32_e32 v86, v82, v86, vcc
	v_cndmask_b32_e64 v139, v230, 0, s[16:17]
	v_cndmask_b32_e64 v141, v231, 0, s[16:17]
;     DI void operator()(AccRef acc, const Unit& u, int wr, int wc, int fr, int fq) const {
;     ...
;             for (int bj = 0; bj < 2; ++bj) {
;                 const f32x4 w0 = *(const f32x4*)(cw + bj * DFF + cg_), w1 = *(const f32x4*)(cw + (size_t)2 * DFF + bj * DFF + cg_),
;                             w2 = *(const f32x4*)(cw + (size_t)4 * DFF + bj * DFF + cg_), wb = *(const f32x4*)(cb + bj * DFF + cg_);
; #pragma unroll
;                 for (int ai = 0; ai < 2; ++ai) {
;                     const int tok0 = 252 * u.pm - 1 + 126 * wr + 64 * ai;
; #pragma unroll
;                     for (int m = 0; m < 4; ++m) {
;                         const int tok = tok0 + 16 * m + fr; const int msk = tok < ML ? 4095 : 255;
;                         const bool hu = (tok & msk) != 0, hd = ((tok + 1) & msk) != 0;
;                         f32x4 r = acc[ai][bj][m][n] * w1 + wb;
;                         f32x4 w0m, w2m;
; #pragma unroll
;                         for (int j = 0; j < 4; ++j) { w0m[j] = hu ? w0[j] : 0.f; w2m[j] = hd ? w2[j] : 0.f; }
; #pragma unroll
;                         for (int j = 0; j < 4; ++j) {
;                             const float su = ((m > 0 || ai == 1) && fr == 15) ? (m > 0 ? acc[ai][bj][(m + 3) & 3][n][j] : acc[0][bj][3][n][j]) : acc[ai][bj][m][n][j];
;                             const float sd = ((m < 3 || ai == 0) && fr == 0) ? (m < 3 ? acc[ai][bj][(m + 1) & 3][n][j] : acc[1][bj][0][n][j]) : acc[ai][bj][m][n][j];
;                             float rj = r[j];
;                             asm("s_nop 1\n\tv_fmac_f32_dpp %0, %1, %2 row_ror:1 row_mask:0xf bank_mask:0xf" : "+v"(rj) : "v"(su), "v"(w0m[j]));
;                             asm("s_nop 1\n\tv_fmac_f32_dpp %0, %1, %2 row_ror:15 row_mask:0xf bank_mask:0xf" : "+v"(rj) : "v"(sd), "v"(w2m[j]));
;                             r[j] = rj; }
;                         if (bj == 0) {
; #pragma unroll
;                             for (int j = 0; j < 4; ++j) o[ai][m][j] = r[j] * __builtin_amdgcn_rcpf(1.f + __builtin_amdgcn_exp2f(-LOG2E * r[j]));
;                         } else o[ai][m] = o[ai][m] * r;
	v_cndmask_b32_e64 v143, v232, 0, s[16:17]
	v_cndmask_b32_e64 v145, v233, 0, s[16:17]
	s_nop 1
	v_fmac_f32_dpp v94, v175, v139 row_ror:15 row_mask:0xf bank_mask:0xf
	s_nop 1
	v_fmac_f32_dpp v95, v174, v141 row_ror:15 row_mask:0xf bank_mask:0xf
	s_nop 1
	v_fmac_f32_dpp v96, v173, v143 row_ror:15 row_mask:0xf bank_mask:0xf
	s_nop 1
	v_fmac_f32_dpp v97, v172, v145 row_ror:15 row_mask:0xf bank_mask:0xf
	v_cndmask_b32_e64 v138, v226, 0, s[18:19]
	v_cndmask_b32_e64 v140, v227, 0, s[18:19]
	v_cndmask_b32_e64 v142, v228, 0, s[18:19]
	v_cndmask_b32_e64 v144, v229, 0, s[18:19]
	v_cndmask_b32_e64 v172, v85, v81, s[4:5]
	v_cndmask_b32_e64 v173, v84, v80, s[4:5]
	v_cndmask_b32_e64 v174, v83, v79, s[4:5]
	v_cndmask_b32_e64 v175, v82, v78, s[4:5]
	s_nop 1
	v_fmac_f32_dpp v90, v86, v138 row_ror:1 row_mask:0xf bank_mask:0xf
	s_nop 1
	v_fmac_f32_dpp v91, v87, v140 row_ror:1 row_mask:0xf bank_mask:0xf
	s_nop 1
	v_fmac_f32_dpp v92, v88, v142 row_ror:1 row_mask:0xf bank_mask:0xf
	s_nop 1
	v_fmac_f32_dpp v93, v89, v144 row_ror:1 row_mask:0xf bank_mask:0xf
	v_pk_fma_f32 v[88:89], v[80:81], v[220:221], v[224:225]
	v_pk_fma_f32 v[86:87], v[78:79], v[218:219], v[222:223]
	v_cndmask_b32_e32 v85, v81, v85, vcc
	v_cndmask_b32_e32 v84, v80, v84, vcc
	v_cndmask_b32_e32 v83, v79, v83, vcc
	v_cndmask_b32_e32 v82, v78, v82, vcc
	v_cndmask_b32_e64 v139, v230, 0, s[20:21]
	v_cndmask_b32_e64 v141, v231, 0, s[20:21]
	v_cndmask_b32_e64 v143, v232, 0, s[20:21]
	v_cndmask_b32_e64 v145, v233, 0, s[20:21]
	s_nop 1
	v_fmac_f32_dpp v90, v175, v139 row_ror:15 row_mask:0xf bank_mask:0xf
	s_nop 1
	v_fmac_f32_dpp v91, v174, v141 row_ror:15 row_mask:0xf bank_mask:0xf
	s_nop 1
	v_fmac_f32_dpp v92, v173, v143 row_ror:15 row_mask:0xf bank_mask:0xf
	s_nop 1
	v_fmac_f32_dpp v93, v172, v145 row_ror:15 row_mask:0xf bank_mask:0xf
	v_cndmask_b32_e64 v138, v226, 0, s[22:23]
	v_cndmask_b32_e64 v140, v227, 0, s[22:23]
	v_cndmask_b32_e64 v142, v228, 0, s[22:23]
	v_cndmask_b32_e64 v144, v229, 0, s[22:23]
	v_cndmask_b32_e64 v172, v81, v77, s[4:5]
	v_cndmask_b32_e64 v173, v80, v76, s[4:5]
	v_cndmask_b32_e64 v174, v79, v75, s[4:5]
	v_cndmask_b32_e64 v175, v78, v74, s[4:5]
	s_nop 1
	v_fmac_f32_dpp v86, v82, v138 row_ror:1 row_mask:0xf bank_mask:0xf
	s_nop 1
	v_fmac_f32_dpp v87, v83, v140 row_ror:1 row_mask:0xf bank_mask:0xf
	s_nop 1
	v_fmac_f32_dpp v88, v84, v142 row_ror:1 row_mask:0xf bank_mask:0xf
	s_nop 1
	v_fmac_f32_dpp v89, v85, v144 row_ror:1 row_mask:0xf bank_mask:0xf
	v_pk_fma_f32 v[84:85], v[76:77], v[220:221], v[224:225]
	v_pk_fma_f32 v[82:83], v[74:75], v[218:219], v[222:223]
	v_cndmask_b32_e32 v81, v77, v81, vcc
	v_cndmask_b32_e32 v80, v76, v80, vcc
	v_cndmask_b32_e32 v79, v75, v79, vcc
	v_cndmask_b32_e32 v78, v74, v78, vcc
	v_cndmask_b32_e64 v139, v230, 0, s[24:25]
	v_cndmask_b32_e64 v141, v231, 0, s[24:25]
	v_cndmask_b32_e64 v143, v232, 0, s[24:25]
	v_cndmask_b32_e64 v145, v233, 0, s[24:25]
	s_nop 1
	v_fmac_f32_dpp v86, v175, v139 row_ror:15 row_mask:0xf bank_mask:0xf
	s_nop 1
	v_fmac_f32_dpp v87, v174, v141 row_ror:15 row_mask:0xf bank_mask:0xf
	s_nop 1
	v_fmac_f32_dpp v88, v173, v143 row_ror:15 row_mask:0xf bank_mask:0xf
	s_nop 1
	v_fmac_f32_dpp v89, v172, v145 row_ror:15 row_mask:0xf bank_mask:0xf
	v_cndmask_b32_e64 v138, v226, 0, s[26:27]
	v_cndmask_b32_e64 v140, v227, 0, s[26:27]
	v_cndmask_b32_e64 v142, v228, 0, s[26:27]
	v_cndmask_b32_e64 v144, v229, 0, s[26:27]
	v_cndmask_b32_e64 v172, v77, v73, s[4:5]
	v_cndmask_b32_e64 v173, v76, v72, s[4:5]
	v_cndmask_b32_e64 v174, v75, v71, s[4:5]
	v_cndmask_b32_e64 v175, v74, v70, s[4:5]
	s_nop 1
	v_fmac_f32_dpp v82, v78, v138 row_ror:1 row_mask:0xf bank_mask:0xf
	s_nop 1
	v_fmac_f32_dpp v83, v79, v140 row_ror:1 row_mask:0xf bank_mask:0xf
	s_nop 1
	v_fmac_f32_dpp v84, v80, v142 row_ror:1 row_mask:0xf bank_mask:0xf
	s_nop 1
	v_fmac_f32_dpp v85, v81, v144 row_ror:1 row_mask:0xf bank_mask:0xf
	v_pk_fma_f32 v[80:81], v[72:73], v[220:221], v[224:225]
	v_pk_fma_f32 v[78:79], v[70:71], v[218:219], v[222:223]
	v_cndmask_b32_e32 v77, v73, v77, vcc
	v_cndmask_b32_e32 v76, v72, v76, vcc
	v_cndmask_b32_e32 v75, v71, v75, vcc
	v_cndmask_b32_e32 v74, v70, v74, vcc
	v_cndmask_b32_e64 v138, v226, 0, s[36:37]
	v_cndmask_b32_e64 v140, v227, 0, s[36:37]
	v_cndmask_b32_e64 v142, v228, 0, s[36:37]
	v_cndmask_b32_e64 v144, v229, 0, s[36:37]
	s_nop 1
	v_fmac_f32_dpp v78, v74, v138 row_ror:1 row_mask:0xf bank_mask:0xf
	s_nop 1
	v_fmac_f32_dpp v79, v75, v140 row_ror:1 row_mask:0xf bank_mask:0xf
	s_nop 1
	v_fmac_f32_dpp v80, v76, v142 row_ror:1 row_mask:0xf bank_mask:0xf
	s_nop 1
	v_fmac_f32_dpp v81, v77, v144 row_ror:1 row_mask:0xf bank_mask:0xf
	v_pk_fma_f32 v[76:77], v[68:69], v[220:221], v[224:225]
	v_pk_fma_f32 v[74:75], v[66:67], v[218:219], v[222:223]
	v_cndmask_b32_e64 v139, v230, 0, s[30:31]
	v_cndmask_b32_e64 v141, v231, 0, s[30:31]
	v_cndmask_b32_e64 v143, v232, 0, s[30:31]
	v_cndmask_b32_e64 v145, v233, 0, s[30:31]
	s_nop 1
	v_fmac_f32_dpp v82, v175, v139 row_ror:15 row_mask:0xf bank_mask:0xf
	s_nop 1
	v_fmac_f32_dpp v83, v174, v141 row_ror:15 row_mask:0xf bank_mask:0xf
	s_nop 1
	v_fmac_f32_dpp v84, v173, v143 row_ror:15 row_mask:0xf bank_mask:0xf
	s_nop 1
	v_fmac_f32_dpp v85, v172, v145 row_ror:15 row_mask:0xf bank_mask:0xf
	v_cndmask_b32_e64 v172, v73, v69, s[4:5]
	v_cndmask_b32_e64 v173, v72, v68, s[4:5]
	v_cndmask_b32_e64 v174, v71, v67, s[4:5]
	v_cndmask_b32_e64 v175, v70, v66, s[4:5]
	v_cndmask_b32_e64 v102, v226, 0, s[28:29]
	v_cndmask_b32_e64 v103, v227, 0, s[28:29]
	v_cndmask_b32_e64 v104, v228, 0, s[28:29]
	v_cndmask_b32_e64 v105, v229, 0, s[28:29]
	v_cndmask_b32_e32 v73, v69, v73, vcc
	v_cndmask_b32_e32 v72, v68, v72, vcc
	v_cndmask_b32_e32 v71, v67, v71, vcc
	v_cndmask_b32_e32 v70, v66, v70, vcc
	s_nop 1
	v_fmac_f32_dpp v74, v70, v102 row_ror:1 row_mask:0xf bank_mask:0xf
	s_nop 1
	v_fmac_f32_dpp v75, v71, v103 row_ror:1 row_mask:0xf bank_mask:0xf
	s_nop 1
	v_fmac_f32_dpp v76, v72, v104 row_ror:1 row_mask:0xf bank_mask:0xf
	s_nop 1
	v_fmac_f32_dpp v77, v73, v105 row_ror:1 row_mask:0xf bank_mask:0xf
	v_cndmask_b32_e64 v139, v230, 0, s[38:39]
	v_cndmask_b32_e64 v141, v231, 0, s[38:39]
	v_cndmask_b32_e64 v143, v232, 0, s[38:39]
	v_cndmask_b32_e64 v145, v233, 0, s[38:39]
	s_nop 1
	v_fmac_f32_dpp v78, v175, v139 row_ror:15 row_mask:0xf bank_mask:0xf
	s_nop 1
	v_fmac_f32_dpp v79, v174, v141 row_ror:15 row_mask:0xf bank_mask:0xf
	s_nop 1
	v_fmac_f32_dpp v80, v173, v143 row_ror:15 row_mask:0xf bank_mask:0xf
	s_nop 1
	v_fmac_f32_dpp v81, v172, v145 row_ror:15 row_mask:0xf bank_mask:0xf
	v_cndmask_b32_e64 v106, v230, 0, s[34:35]
	v_cndmask_b32_e64 v107, v231, 0, s[34:35]
	v_cndmask_b32_e64 v108, v232, 0, s[34:35]
	v_cndmask_b32_e64 v109, v233, 0, s[34:35]
	s_nop 1
	v_fmac_f32_dpp v74, v66, v106 row_ror:15 row_mask:0xf bank_mask:0xf
	s_nop 1
	v_fmac_f32_dpp v75, v67, v107 row_ror:15 row_mask:0xf bank_mask:0xf
	s_nop 1
	v_fmac_f32_dpp v76, v68, v108 row_ror:15 row_mask:0xf bank_mask:0xf
	s_nop 1
	v_fmac_f32_dpp v77, v69, v109 row_ror:15 row_mask:0xf bank_mask:0xf
	s_and_saveexec_b64 s[0:1], s[54:55]
	s_cbranch_execz .LBB0_1604
; DI unsigned pk2(float a, float b) { f32x2 v = {a, b}; bfv2 r = __builtin_convertvector(v, bfv2); return __builtin_bit_cast(unsigned, r); }
;     DI void operator()(AccRef acc, const Unit& u, int wr, int wc, int fr, int fq) const {
;     ...
;                             for (int j = 0; j < 4; ++j) o[ai][m][j] = r[j] * __builtin_amdgcn_rcpf(1.f + __builtin_amdgcn_exp2f(-LOG2E * r[j]));
;     ...
;                     if (li >= 1 && li <= 126 && tok < Mq) { u32x2 v; v.x = pk2(o[ai][m][0], o[ai][m][1]); v.y = pk2(o[ai][m][2], o[ai][m][3]);
;                         *(u32x2*)(ACT + (size_t)tok * DFF + cg_) = v; } }
	v_mul_f32_e32 v66, 0xbfb8aa3b, v154
	v_mul_f32_e32 v67, 0xbfb8aa3b, v155
	v_mul_f32_e32 v68, 0xbfb8aa3b, v152
	v_mul_f32_e32 v69, 0xbfb8aa3b, v153
	v_exp_f32_e32 v66, v66
	v_exp_f32_e32 v67, v67
	v_exp_f32_e32 v68, v68
	v_exp_f32_e32 v69, v69
	v_add_f32_e32 v66, 1.0, v66
	v_add_f32_e32 v67, 1.0, v67
	v_add_f32_e32 v68, 1.0, v68
	v_add_f32_e32 v69, 1.0, v69
	v_rcp_f32_e32 v66, v66
	v_rcp_f32_e32 v67, v67
	v_rcp_f32_e32 v68, v68
	v_rcp_f32_e32 v69, v69
	s_movk_i32 s33, 0x2c00
	v_pk_mul_f32 v[66:67], v[154:155], v[66:67]
	v_pk_mul_f32 v[68:69], v[152:153], v[68:69]
	s_nop 0
	v_pk_mul_f32 v[68:69], v[68:69], v[136:137]
	v_pk_mul_f32 v[66:67], v[66:67], v[134:135]
	s_nop 0
	v_cvt_pk_bf16_f32 v66, v66, v67
	v_cvt_pk_bf16_f32 v67, v68, v69
	v_mov_b64_e32 v[68:69], s[92:93]
	v_mad_i64_i32 v[68:69], s[42:43], v0, s33, v[68:69]
	v_lshl_add_u64 v[68:69], v[146:147], 1, v[68:69]
	global_store_dwordx2 v[68:69], v[66:67], off

;     DI void operator()(AccRef acc, const Unit& u, int wr, int wc, int fr, int fq) const {
;     ...
;         for (int n = 0; n < 2; ++n) {
;             const int cg_ = 128 * u.pn + 32 * wc + 8 * fq + 4 * n;
;             f32x4 o[2][4];
; #pragma unroll
;             for (int bj = 0; bj < 2; ++bj) {
;                 const f32x4 w0 = *(const f32x4*)(cw + bj * DFF + cg_), w1 = *(const f32x4*)(cw + (size_t)2 * DFF + bj * DFF + cg_),
;                             w2 = *(const f32x4*)(cw + (size_t)4 * DFF + bj * DFF + cg_), wb = *(const f32x4*)(cb + bj * DFF + cg_);
; #pragma unroll
;                 for (int ai = 0; ai < 2; ++ai) {
;                     const int tok0 = 252 * u.pm - 1 + 126 * wr + 64 * ai;
; #pragma unroll
;                     for (int m = 0; m < 4; ++m) {
;                         const int tok = tok0 + 16 * m + fr; const int msk = tok < ML ? 4095 : 255;
;                         const bool hu = (tok & msk) != 0, hd = ((tok + 1) & msk) != 0;
;                         f32x4 r = acc[ai][bj][m][n] * w1 + wb;
;                         f32x4 w0m, w2m;
; #pragma unroll
;                         for (int j = 0; j < 4; ++j) { w0m[j] = hu ? w0[j] : 0.f; w2m[j] = hd ? w2[j] : 0.f; }
; #pragma unroll
;                         for (int j = 0; j < 4; ++j) {
;                             const float su = ((m > 0 || ai == 1) && fr == 15) ? (m > 0 ? acc[ai][bj][(m + 3) & 3][n][j] : acc[0][bj][3][n][j]) : acc[ai][bj][m][n][j];
;                             const float sd = ((m < 3 || ai == 0) && fr == 0) ? (m < 3 ? acc[ai][bj][(m + 1) & 3][n][j] : acc[1][bj][0][n][j]) : acc[ai][bj][m][n][j];
;                             float rj = r[j];
;                             asm("s_nop 1\n\tv_fmac_f32_dpp %0, %1, %2 row_ror:1 row_mask:0xf bank_mask:0xf" : "+v"(rj) : "v"(su), "v"(w0m[j]));
;                             asm("s_nop 1\n\tv_fmac_f32_dpp %0, %1, %2 row_ror:15 row_mask:0xf bank_mask:0xf" : "+v"(rj) : "v"(sd), "v"(w2m[j]));
;                             r[j] = rj; }
.LBB0_1618:
	s_or_b64 exec, exec, s[0:1]
	v_or_b32_e32 v66, 4, v146
	v_ashrrev_i32_e32 v67, 31, v66
	v_lshlrev_b64 v[66:67], 2, v[66:67]
	v_lshl_add_u64 v[100:101], s[84:85], 0, v[66:67]
	v_lshl_add_u64 v[98:99], s[50:51], 0, v[66:67]
	v_cndmask_b32_e64 v94, v65, v61, s[4:5]
	v_cndmask_b32_e64 v95, v64, v60, s[4:5]
	v_cndmask_b32_e64 v96, v63, v59, s[4:5]
	v_cndmask_b32_e64 v97, v62, v58, s[4:5]
	v_cndmask_b32_e64 v103, v60, v56, s[4:5]
	v_cndmask_b32_e64 v102, v61, v57, s[4:5]
	v_cndmask_b32_e64 v105, v58, v54, s[4:5]
	v_cndmask_b32_e64 v104, v59, v55, s[4:5]
	s_movk_i32 s33, 0x5000
	v_cndmask_b32_e64 v86, v234, 0, s[6:7]
	v_cndmask_b32_e64 v88, v235, 0, s[6:7]
	v_cndmask_b32_e64 v87, v242, 0, s[8:9]
	v_pk_fma_f32 v[84:85], v[62:63], v[238:239], v[246:247]
	v_cndmask_b32_e64 v89, v243, 0, s[8:9]
	v_pk_fma_f32 v[82:83], v[64:65], v[240:241], v[248:249]
	s_nop 1
	v_fmac_f32_dpp v84, v62, v86 row_ror:1 row_mask:0xf bank_mask:0xf
	s_nop 1
	v_fmac_f32_dpp v85, v63, v88 row_ror:1 row_mask:0xf bank_mask:0xf
	v_cndmask_b32_e64 v90, v236, 0, s[6:7]
	v_cndmask_b32_e64 v92, v237, 0, s[6:7]
	s_nop 1
	v_fmac_f32_dpp v84, v97, v87 row_ror:15 row_mask:0xf bank_mask:0xf
	s_nop 1
	v_fmac_f32_dpp v85, v96, v89 row_ror:15 row_mask:0xf bank_mask:0xf
	s_nop 1
	v_fmac_f32_dpp v82, v64, v90 row_ror:1 row_mask:0xf bank_mask:0xf
	s_nop 1
	v_fmac_f32_dpp v83, v65, v92 row_ror:1 row_mask:0xf bank_mask:0xf
	v_pk_fma_f32 v[86:87], v[60:61], v[240:241], v[248:249]
	v_pk_fma_f32 v[88:89], v[58:59], v[238:239], v[246:247]
	v_cndmask_b32_e32 v63, v59, v63, vcc
	v_cndmask_b32_e32 v62, v58, v62, vcc
	v_cndmask_b32_e64 v91, v244, 0, s[8:9]
	v_cndmask_b32_e64 v93, v245, 0, s[8:9]
	s_nop 1
	v_fmac_f32_dpp v82, v95, v91 row_ror:15 row_mask:0xf bank_mask:0xf
	s_nop 1
	v_fmac_f32_dpp v83, v94, v93 row_ror:15 row_mask:0xf bank_mask:0xf
	v_cndmask_b32_e64 v90, v234, 0, s[10:11]
	v_cndmask_b32_e64 v92, v235, 0, s[10:11]
	v_cndmask_b32_e64 v94, v236, 0, s[10:11]
	v_cndmask_b32_e64 v95, v244, 0, s[12:13]
	v_cndmask_b32_e32 v65, v61, v65, vcc
	v_cndmask_b32_e32 v64, v60, v64, vcc
	s_nop 1
	v_fmac_f32_dpp v88, v62, v90 row_ror:1 row_mask:0xf bank_mask:0xf
	s_nop 1
	v_fmac_f32_dpp v89, v63, v92 row_ror:1 row_mask:0xf bank_mask:0xf
	s_nop 1
	v_fmac_f32_dpp v86, v64, v94 row_ror:1 row_mask:0xf bank_mask:0xf
	v_pk_fma_f32 v[62:63], v[56:57], v[240:241], v[248:249]
	v_cndmask_b32_e64 v91, v242, 0, s[12:13]
	v_cndmask_b32_e64 v96, v237, 0, s[10:11]
	v_cndmask_b32_e64 v97, v245, 0, s[12:13]
	s_nop 1
	v_fmac_f32_dpp v86, v103, v95 row_ror:15 row_mask:0xf bank_mask:0xf
	s_nop 1
	v_fmac_f32_dpp v87, v65, v96 row_ror:1 row_mask:0xf bank_mask:0xf
	v_cndmask_b32_e64 v94, v236, 0, s[14:15]
	v_cndmask_b32_e64 v95, v244, 0, s[16:17]
	v_pk_fma_f32 v[64:65], v[54:55], v[238:239], v[246:247]
	v_cndmask_b32_e32 v60, v56, v60, vcc
	s_nop 1
	v_fmac_f32_dpp v62, v60, v94 row_ror:1 row_mask:0xf bank_mask:0xf
	v_cndmask_b32_e64 v93, v243, 0, s[12:13]
	s_nop 1
	v_fmac_f32_dpp v88, v105, v91 row_ror:15 row_mask:0xf bank_mask:0xf
	s_nop 1
	v_fmac_f32_dpp v87, v102, v97 row_ror:15 row_mask:0xf bank_mask:0xf
	v_cndmask_b32_e64 v90, v234, 0, s[14:15]
	v_cndmask_b32_e64 v91, v242, 0, s[16:17]
	v_cndmask_b32_e64 v96, v237, 0, s[14:15]
	v_cndmask_b32_e64 v97, v245, 0, s[16:17]
	v_cndmask_b32_e32 v61, v57, v61, vcc
	v_cndmask_b32_e32 v58, v54, v58, vcc
	v_cndmask_b32_e64 v103, v56, v52, s[4:5]
	s_nop 1
	v_fmac_f32_dpp v64, v58, v90 row_ror:1 row_mask:0xf bank_mask:0xf
	s_nop 1
	v_fmac_f32_dpp v62, v103, v95 row_ror:15 row_mask:0xf bank_mask:0xf
	s_nop 1
	v_fmac_f32_dpp v63, v61, v96 row_ror:1 row_mask:0xf bank_mask:0xf
	v_pk_fma_f32 v[94:95], v[52:53], v[240:241], v[248:249]
	s_nop 1
	v_fmac_f32_dpp v89, v104, v93 row_ror:15 row_mask:0xf bank_mask:0xf
	v_cndmask_b32_e64 v92, v235, 0, s[14:15]
	v_cndmask_b32_e64 v93, v243, 0, s[16:17]
	v_cndmask_b32_e32 v59, v55, v59, vcc
	v_cndmask_b32_e64 v102, v57, v53, s[4:5]
	v_cndmask_b32_e64 v105, v54, v50, s[4:5]
	s_nop 1
	v_fmac_f32_dpp v64, v105, v91 row_ror:15 row_mask:0xf bank_mask:0xf
	s_nop 1
	v_fmac_f32_dpp v65, v59, v92 row_ror:1 row_mask:0xf bank_mask:0xf
	s_nop 1
	v_fmac_f32_dpp v63, v102, v97 row_ror:15 row_mask:0xf bank_mask:0xf
	v_cndmask_b32_e64 v90, v236, 0, s[18:19]
	v_cndmask_b32_e64 v91, v244, 0, s[20:21]
	v_pk_fma_f32 v[96:97], v[50:51], v[238:239], v[246:247]
	v_cndmask_b32_e32 v56, v52, v56, vcc
	s_nop 1
	v_fmac_f32_dpp v94, v56, v90 row_ror:1 row_mask:0xf bank_mask:0xf
	v_cndmask_b32_e64 v104, v55, v51, s[4:5]
	s_nop 1
	v_fmac_f32_dpp v65, v104, v93 row_ror:15 row_mask:0xf bank_mask:0xf
	v_cndmask_b32_e64 v58, v234, 0, s[18:19]
	v_cndmask_b32_e64 v59, v242, 0, s[20:21]
	v_cndmask_b32_e64 v92, v237, 0, s[18:19]
	v_cndmask_b32_e64 v93, v245, 0, s[20:21]
	v_cndmask_b32_e32 v57, v53, v57, vcc
	v_cndmask_b32_e32 v54, v50, v54, vcc
	v_cndmask_b32_e64 v103, v52, v48, s[4:5]
	s_nop 1
	v_fmac_f32_dpp v96, v54, v58 row_ror:1 row_mask:0xf bank_mask:0xf
	s_nop 1
	v_fmac_f32_dpp v94, v103, v91 row_ror:15 row_mask:0xf bank_mask:0xf
	s_nop 1
	v_fmac_f32_dpp v95, v57, v92 row_ror:1 row_mask:0xf bank_mask:0xf
	v_pk_fma_f32 v[90:91], v[48:49], v[240:241], v[248:249]
	v_cndmask_b32_e64 v60, v235, 0, s[18:19]
	v_cndmask_b32_e64 v61, v243, 0, s[20:21]
	v_cndmask_b32_e32 v55, v51, v55, vcc
	v_cndmask_b32_e64 v102, v53, v49, s[4:5]
	v_cndmask_b32_e64 v105, v50, v46, s[4:5]
	s_nop 1
	v_fmac_f32_dpp v96, v105, v59 row_ror:15 row_mask:0xf bank_mask:0xf
	s_nop 1
	v_fmac_f32_dpp v97, v55, v60 row_ror:1 row_mask:0xf bank_mask:0xf
	s_nop 1
	v_fmac_f32_dpp v95, v102, v93 row_ror:15 row_mask:0xf bank_mask:0xf
	v_cndmask_b32_e64 v58, v236, 0, s[22:23]
	v_cndmask_b32_e64 v59, v244, 0, s[24:25]
;     DI void operator()(AccRef acc, const Unit& u, int wr, int wc, int fr, int fq) const {
;     ...
;         for (int n = 0; n < 2; ++n) {
;             const int cg_ = 128 * u.pn + 32 * wc + 8 * fq + 4 * n;
;             f32x4 o[2][4];
; #pragma unroll
;             for (int bj = 0; bj < 2; ++bj) {
;                 const f32x4 w0 = *(const f32x4*)(cw + bj * DFF + cg_), w1 = *(const f32x4*)(cw + (size_t)2 * DFF + bj * DFF + cg_),
;                             w2 = *(const f32x4*)(cw + (size_t)4 * DFF + bj * DFF + cg_), wb = *(const f32x4*)(cb + bj * DFF + cg_);
; #pragma unroll
;                 for (int ai = 0; ai < 2; ++ai) {
;                     const int tok0 = 252 * u.pm - 1 + 126 * wr + 64 * ai;
; #pragma unroll
;                     for (int m = 0; m < 4; ++m) {
;                         const int tok = tok0 + 16 * m + fr; const int msk = tok < ML ? 4095 : 255;
;                         const bool hu = (tok & msk) != 0, hd = ((tok + 1) & msk) != 0;
;                         f32x4 r = acc[ai][bj][m][n] * w1 + wb;
;                         f32x4 w0m, w2m;
; #pragma unroll
;                         for (int j = 0; j < 4; ++j) { w0m[j] = hu ? w0[j] : 0.f; w2m[j] = hd ? w2[j] : 0.f; }
; #pragma unroll
;                         for (int j = 0; j < 4; ++j) {
;                             const float su = ((m > 0 || ai == 1) && fr == 15) ? (m > 0 ? acc[ai][bj][(m + 3) & 3][n][j] : acc[0][bj][3][n][j]) : acc[ai][bj][m][n][j];
;                             const float sd = ((m < 3 || ai == 0) && fr == 0) ? (m < 3 ? acc[ai][bj][(m + 1) & 3][n][j] : acc[1][bj][0][n][j]) : acc[ai][bj][m][n][j];
;                             float rj = r[j];
;                             asm("s_nop 1\n\tv_fmac_f32_dpp %0, %1, %2 row_ror:1 row_mask:0xf bank_mask:0xf" : "+v"(rj) : "v"(su), "v"(w0m[j]));
;                             asm("s_nop 1\n\tv_fmac_f32_dpp %0, %1, %2 row_ror:15 row_mask:0xf bank_mask:0xf" : "+v"(rj) : "v"(sd), "v"(w2m[j]));
;                             r[j] = rj; }
	v_pk_fma_f32 v[92:93], v[46:47], v[238:239], v[246:247]
	v_cndmask_b32_e32 v52, v48, v52, vcc
	s_nop 1
	v_fmac_f32_dpp v90, v52, v58 row_ror:1 row_mask:0xf bank_mask:0xf
	v_cndmask_b32_e64 v104, v51, v47, s[4:5]
	s_nop 1
	v_fmac_f32_dpp v97, v104, v61 row_ror:15 row_mask:0xf bank_mask:0xf
	v_cndmask_b32_e64 v54, v234, 0, s[22:23]
	v_cndmask_b32_e64 v55, v242, 0, s[24:25]
	v_cndmask_b32_e64 v60, v237, 0, s[22:23]
	v_cndmask_b32_e64 v61, v245, 0, s[24:25]
	v_cndmask_b32_e32 v53, v49, v53, vcc
	v_cndmask_b32_e32 v50, v46, v50, vcc
	v_cndmask_b32_e64 v103, v48, v44, s[4:5]
	s_nop 1
	v_fmac_f32_dpp v92, v50, v54 row_ror:1 row_mask:0xf bank_mask:0xf
	s_nop 1
	v_fmac_f32_dpp v90, v103, v59 row_ror:15 row_mask:0xf bank_mask:0xf
	s_nop 1
	v_fmac_f32_dpp v91, v53, v60 row_ror:1 row_mask:0xf bank_mask:0xf
	v_pk_fma_f32 v[58:59], v[44:45], v[240:241], v[248:249]
	v_cndmask_b32_e64 v102, v49, v45, s[4:5]
	v_cndmask_b32_e64 v105, v46, v42, s[4:5]
	s_nop 1
	v_fmac_f32_dpp v92, v105, v55 row_ror:15 row_mask:0xf bank_mask:0xf
	s_nop 1
	v_fmac_f32_dpp v91, v102, v61 row_ror:15 row_mask:0xf bank_mask:0xf
	v_cndmask_b32_e64 v54, v236, 0, s[26:27]
	v_cndmask_b32_e64 v55, v244, 0, s[30:31]
	v_pk_fma_f32 v[60:61], v[42:43], v[238:239], v[246:247]
	v_cndmask_b32_e32 v48, v44, v48, vcc
	s_nop 1
	v_fmac_f32_dpp v58, v48, v54 row_ror:1 row_mask:0xf bank_mask:0xf
	v_cndmask_b32_e64 v56, v235, 0, s[22:23]
	v_cndmask_b32_e64 v57, v243, 0, s[24:25]
	v_cndmask_b32_e32 v51, v47, v51, vcc
	v_cndmask_b32_e64 v104, v47, v43, s[4:5]
	s_nop 1
	v_fmac_f32_dpp v93, v51, v56 row_ror:1 row_mask:0xf bank_mask:0xf
	v_cndmask_b32_e64 v52, v235, 0, s[26:27]
	v_cndmask_b32_e64 v53, v243, 0, s[30:31]
	v_cndmask_b32_e32 v47, v43, v47, vcc
	v_cndmask_b32_e64 v103, v44, v40, s[4:5]
	s_nop 1
	v_fmac_f32_dpp v61, v47, v52 row_ror:1 row_mask:0xf bank_mask:0xf
	s_nop 1
	v_fmac_f32_dpp v58, v103, v55 row_ror:15 row_mask:0xf bank_mask:0xf
	v_pk_fma_f32 v[54:55], v[40:41], v[240:241], v[248:249]
	s_nop 1
	v_fmac_f32_dpp v93, v104, v57 row_ror:15 row_mask:0xf bank_mask:0xf
	v_cndmask_b32_e64 v56, v237, 0, s[26:27]
	v_cndmask_b32_e64 v57, v245, 0, s[30:31]
	v_cndmask_b32_e32 v49, v45, v49, vcc
	v_cndmask_b32_e64 v102, v45, v41, s[4:5]
	v_cndmask_b32_e64 v104, v43, v39, s[4:5]
	s_nop 1
	v_fmac_f32_dpp v61, v104, v53 row_ror:15 row_mask:0xf bank_mask:0xf
	s_nop 1
	v_fmac_f32_dpp v59, v49, v56 row_ror:1 row_mask:0xf bank_mask:0xf
	v_cndmask_b32_e64 v52, v237, 0, s[36:37]
	v_cndmask_b32_e64 v53, v245, 0, s[38:39]
	v_cndmask_b32_e32 v45, v41, v45, vcc
	s_nop 1
	v_fmac_f32_dpp v55, v45, v52 row_ror:1 row_mask:0xf bank_mask:0xf
	v_cndmask_b32_e64 v50, v234, 0, s[26:27]
	v_cndmask_b32_e32 v46, v42, v46, vcc
	v_cndmask_b32_e64 v105, v42, v38, s[4:5]
	s_nop 1
	v_fmac_f32_dpp v60, v46, v50 row_ror:1 row_mask:0xf bank_mask:0xf
	s_nop 1
	v_fmac_f32_dpp v59, v102, v57 row_ror:15 row_mask:0xf bank_mask:0xf
	v_pk_fma_f32 v[56:57], v[38:39], v[238:239], v[246:247]
	v_cndmask_b32_e32 v42, v38, v42, vcc
	v_cndmask_b32_e64 v102, v41, v37, s[4:5]
	s_nop 1
	v_fmac_f32_dpp v55, v102, v53 row_ror:15 row_mask:0xf bank_mask:0xf
	v_pk_fma_f32 v[52:53], v[34:35], v[238:239], v[246:247]
	v_cndmask_b32_e64 v51, v242, 0, s[30:31]
	s_nop 1
	v_fmac_f32_dpp v60, v105, v51 row_ror:15 row_mask:0xf bank_mask:0xf
	v_cndmask_b32_e64 v46, v234, 0, s[36:37]
	v_cndmask_b32_e32 v44, v40, v44, vcc
	v_cndmask_b32_e32 v43, v39, v43, vcc
	v_cndmask_b32_e64 v105, v38, v34, s[4:5]
	s_nop 1
	v_fmac_f32_dpp v56, v42, v46 row_ror:1 row_mask:0xf bank_mask:0xf
	v_cndmask_b32_e64 v42, v234, 0, s[28:29]
	v_cndmask_b32_e32 v38, v34, v38, vcc
	s_nop 1
	v_fmac_f32_dpp v52, v38, v42 row_ror:1 row_mask:0xf bank_mask:0xf
	v_cndmask_b32_e64 v48, v235, 0, s[36:37]
	v_cndmask_b32_e64 v50, v236, 0, s[36:37]
	v_cndmask_b32_e64 v104, v39, v35, s[4:5]
	s_nop 1
	v_fmac_f32_dpp v57, v43, v48 row_ror:1 row_mask:0xf bank_mask:0xf
	s_nop 1
	v_fmac_f32_dpp v54, v44, v50 row_ror:1 row_mask:0xf bank_mask:0xf
	v_cndmask_b32_e64 v43, v242, 0, s[34:35]
	v_cndmask_b32_e64 v44, v235, 0, s[28:29]
	v_cndmask_b32_e32 v39, v35, v39, vcc
	s_nop 1
	v_fmac_f32_dpp v52, v34, v43 row_ror:15 row_mask:0xf bank_mask:0xf
	s_nop 1
	v_fmac_f32_dpp v53, v39, v44 row_ror:1 row_mask:0xf bank_mask:0xf
	v_add_co_u32_e64 v34, s[0:1], s33, v100
	v_cndmask_b32_e64 v51, v244, 0, s[38:39]
	v_cndmask_b32_e64 v45, v243, 0, s[34:35]
	s_nop 1
	v_fmac_f32_dpp v53, v35, v45 row_ror:15 row_mask:0xf bank_mask:0xf
	v_addc_co_u32_e64 v35, s[0:1], 0, v101, s[0:1]
	v_cndmask_b32_e64 v47, v242, 0, s[38:39]
	v_cndmask_b32_e64 v49, v243, 0, s[38:39]
	v_cndmask_b32_e64 v103, v40, v36, s[4:5]
	s_nop 1
	v_fmac_f32_dpp v54, v103, v51 row_ror:15 row_mask:0xf bank_mask:0xf
	v_pk_fma_f32 v[50:51], v[36:37], v[240:241], v[248:249]
	v_add_co_u32_e64 v42, s[0:1], s33, v98
	s_nop 1
	v_fmac_f32_dpp v56, v105, v47 row_ror:15 row_mask:0xf bank_mask:0xf
	s_nop 1
	v_fmac_f32_dpp v57, v104, v49 row_ror:15 row_mask:0xf bank_mask:0xf
	v_cndmask_b32_e64 v46, v236, 0, s[28:29]
	v_cndmask_b32_e64 v47, v244, 0, s[34:35]
	v_cndmask_b32_e64 v48, v237, 0, s[28:29]
	v_cndmask_b32_e64 v49, v245, 0, s[34:35]
	v_cndmask_b32_e32 v41, v37, v41, vcc
	v_cndmask_b32_e32 v40, v36, v40, vcc
	s_nop 1
	v_fmac_f32_dpp v50, v40, v46 row_ror:1 row_mask:0xf bank_mask:0xf
	s_nop 1
	v_fmac_f32_dpp v51, v41, v48 row_ror:1 row_mask:0xf bank_mask:0xf
	v_addc_co_u32_e64 v43, s[0:1], 0, v99, s[0:1]
	s_nop 1
	v_fmac_f32_dpp v50, v36, v47 row_ror:15 row_mask:0xf bank_mask:0xf
	s_nop 1
	v_fmac_f32_dpp v51, v37, v49 row_ror:15 row_mask:0xf bank_mask:0xf
	v_cndmask_b32_e64 v78, v33, v29, s[4:5]
	s_nop 0
	s_nop 0
	v_cndmask_b32_e64 v79, v32, v28, s[4:5]
;     DI void operator()(AccRef acc, const Unit& u, int wr, int wc, int fr, int fq) const {
;     ...
;             for (int bj = 0; bj < 2; ++bj) {
;                 const f32x4 w0 = *(const f32x4*)(cw + bj * DFF + cg_), w1 = *(const f32x4*)(cw + (size_t)2 * DFF + bj * DFF + cg_),
;                             w2 = *(const f32x4*)(cw + (size_t)4 * DFF + bj * DFF + cg_), wb = *(const f32x4*)(cb + bj * DFF + cg_);
; #pragma unroll
;                 for (int ai = 0; ai < 2; ++ai) {
;                     const int tok0 = 252 * u.pm - 1 + 126 * wr + 64 * ai;
; #pragma unroll
;                     for (int m = 0; m < 4; ++m) {
;                         const int tok = tok0 + 16 * m + fr; const int msk = tok < ML ? 4095 : 255;
;                         const bool hu = (tok & msk) != 0, hd = ((tok + 1) & msk) != 0;
;                         f32x4 r = acc[ai][bj][m][n] * w1 + wb;
;                         f32x4 w0m, w2m;
; #pragma unroll
;                         for (int j = 0; j < 4; ++j) { w0m[j] = hu ? w0[j] : 0.f; w2m[j] = hd ? w2[j] : 0.f; }
; #pragma unroll
;                         for (int j = 0; j < 4; ++j) {
;                             const float su = ((m > 0 || ai == 1) && fr == 15) ? (m > 0 ? acc[ai][bj][(m + 3) & 3][n][j] : acc[0][bj][3][n][j]) : acc[ai][bj][m][n][j];
;                             const float sd = ((m < 3 || ai == 0) && fr == 0) ? (m < 3 ? acc[ai][bj][(m + 1) & 3][n][j] : acc[1][bj][0][n][j]) : acc[ai][bj][m][n][j];
;                             float rj = r[j];
;                             asm("s_nop 1\n\tv_fmac_f32_dpp %0, %1, %2 row_ror:1 row_mask:0xf bank_mask:0xf" : "+v"(rj) : "v"(su), "v"(w0m[j]));
;                             asm("s_nop 1\n\tv_fmac_f32_dpp %0, %1, %2 row_ror:15 row_mask:0xf bank_mask:0xf" : "+v"(rj) : "v"(sd), "v"(w2m[j]));
;                             r[j] = rj; }
	v_cndmask_b32_e64 v80, v31, v27, s[4:5]
	v_cndmask_b32_e64 v81, v30, v26, s[4:5]
	v_cndmask_b32_e64 v98, v29, v25, s[4:5]
	v_cndmask_b32_e64 v99, v28, v24, s[4:5]
	v_cndmask_b32_e64 v100, v27, v23, s[4:5]
	v_cndmask_b32_e64 v101, v26, v22, s[4:5]
	v_cndmask_b32_e64 v66, v250, 0, s[6:7]
	v_cndmask_b32_e64 v68, v251, 0, s[6:7]
	v_cndmask_b32_e64 v67, v212, 0, s[8:9]
	v_pk_fma_f32 v[70:71], v[30:31], v[208:209], v[196:197]
	v_cndmask_b32_e64 v69, v213, 0, s[8:9]
	v_pk_fma_f32 v[72:73], v[32:33], v[210:211], v[198:199]
	s_nop 1
	v_fmac_f32_dpp v70, v30, v66 row_ror:1 row_mask:0xf bank_mask:0xf
	s_nop 1
	v_fmac_f32_dpp v71, v31, v68 row_ror:1 row_mask:0xf bank_mask:0xf
	v_cndmask_b32_e64 v74, v252, 0, s[6:7]
	v_cndmask_b32_e64 v76, v253, 0, s[6:7]
	s_nop 1
	v_fmac_f32_dpp v70, v81, v67 row_ror:15 row_mask:0xf bank_mask:0xf
	s_nop 1
	v_fmac_f32_dpp v71, v80, v69 row_ror:15 row_mask:0xf bank_mask:0xf
	s_nop 1
	v_fmac_f32_dpp v72, v32, v74 row_ror:1 row_mask:0xf bank_mask:0xf
	s_nop 1
	v_fmac_f32_dpp v73, v33, v76 row_ror:1 row_mask:0xf bank_mask:0xf
	v_pk_fma_f32 v[68:69], v[28:29], v[210:211], v[198:199]
	v_pk_fma_f32 v[66:67], v[26:27], v[208:209], v[196:197]
	v_cndmask_b32_e32 v33, v29, v33, vcc
	v_cndmask_b32_e32 v32, v28, v32, vcc
	v_cndmask_b32_e32 v31, v27, v31, vcc
	v_cndmask_b32_e32 v30, v26, v30, vcc
	v_cndmask_b32_e64 v75, v214, 0, s[8:9]
	v_cndmask_b32_e64 v77, v215, 0, s[8:9]
	s_nop 1
	v_fmac_f32_dpp v73, v78, v77 row_ror:15 row_mask:0xf bank_mask:0xf
	v_cndmask_b32_e64 v74, v250, 0, s[10:11]
	v_cndmask_b32_e64 v76, v251, 0, s[10:11]
	v_cndmask_b32_e64 v78, v252, 0, s[10:11]
	v_cndmask_b32_e64 v80, v253, 0, s[10:11]
	s_nop 1
	v_fmac_f32_dpp v66, v30, v74 row_ror:1 row_mask:0xf bank_mask:0xf
	s_nop 1
	v_fmac_f32_dpp v67, v31, v76 row_ror:1 row_mask:0xf bank_mask:0xf
	s_nop 1
	v_fmac_f32_dpp v68, v32, v78 row_ror:1 row_mask:0xf bank_mask:0xf
	s_nop 1
	v_fmac_f32_dpp v69, v33, v80 row_ror:1 row_mask:0xf bank_mask:0xf
	v_pk_fma_f32 v[32:33], v[24:25], v[210:211], v[198:199]
	v_pk_fma_f32 v[30:31], v[22:23], v[208:209], v[196:197]
	v_cndmask_b32_e32 v29, v25, v29, vcc
	v_cndmask_b32_e32 v28, v24, v28, vcc
	v_cndmask_b32_e32 v27, v23, v27, vcc
	v_cndmask_b32_e32 v26, v22, v26, vcc
	s_nop 1
	v_fmac_f32_dpp v72, v79, v75 row_ror:15 row_mask:0xf bank_mask:0xf
	v_cndmask_b32_e64 v75, v212, 0, s[12:13]
	v_cndmask_b32_e64 v77, v213, 0, s[12:13]
	v_cndmask_b32_e64 v79, v214, 0, s[12:13]
	v_cndmask_b32_e64 v81, v215, 0, s[12:13]
	s_nop 1
	v_fmac_f32_dpp v66, v101, v75 row_ror:15 row_mask:0xf bank_mask:0xf
	s_nop 1
	v_fmac_f32_dpp v67, v100, v77 row_ror:15 row_mask:0xf bank_mask:0xf
	s_nop 1
	v_fmac_f32_dpp v68, v99, v79 row_ror:15 row_mask:0xf bank_mask:0xf
	s_nop 1
	v_fmac_f32_dpp v69, v98, v81 row_ror:15 row_mask:0xf bank_mask:0xf
	v_cndmask_b32_e64 v74, v250, 0, s[14:15]
	v_cndmask_b32_e64 v76, v251, 0, s[14:15]
	v_cndmask_b32_e64 v78, v252, 0, s[14:15]
	v_cndmask_b32_e64 v80, v253, 0, s[14:15]
	v_cndmask_b32_e64 v98, v25, v21, s[4:5]
	v_cndmask_b32_e64 v99, v24, v20, s[4:5]
	v_cndmask_b32_e64 v100, v23, v19, s[4:5]
	v_cndmask_b32_e64 v101, v22, v18, s[4:5]
	s_nop 1
	v_fmac_f32_dpp v30, v26, v74 row_ror:1 row_mask:0xf bank_mask:0xf
	s_nop 1
	v_fmac_f32_dpp v31, v27, v76 row_ror:1 row_mask:0xf bank_mask:0xf
	s_nop 1
	v_fmac_f32_dpp v32, v28, v78 row_ror:1 row_mask:0xf bank_mask:0xf
	s_nop 1
	v_fmac_f32_dpp v33, v29, v80 row_ror:1 row_mask:0xf bank_mask:0xf
	v_pk_fma_f32 v[28:29], v[20:21], v[210:211], v[198:199]
	v_pk_fma_f32 v[26:27], v[18:19], v[208:209], v[196:197]
	v_cndmask_b32_e32 v25, v21, v25, vcc
	v_cndmask_b32_e32 v24, v20, v24, vcc
	v_cndmask_b32_e32 v23, v19, v23, vcc
	v_cndmask_b32_e32 v22, v18, v22, vcc
	v_cndmask_b32_e64 v75, v212, 0, s[16:17]
	v_cndmask_b32_e64 v77, v213, 0, s[16:17]
	v_cndmask_b32_e64 v79, v214, 0, s[16:17]
	v_cndmask_b32_e64 v81, v215, 0, s[16:17]
	s_nop 1
	v_fmac_f32_dpp v30, v101, v75 row_ror:15 row_mask:0xf bank_mask:0xf
	s_nop 1
	v_fmac_f32_dpp v31, v100, v77 row_ror:15 row_mask:0xf bank_mask:0xf
	s_nop 1
	v_fmac_f32_dpp v32, v99, v79 row_ror:15 row_mask:0xf bank_mask:0xf
	s_nop 1
	v_fmac_f32_dpp v33, v98, v81 row_ror:15 row_mask:0xf bank_mask:0xf
	v_cndmask_b32_e64 v74, v250, 0, s[18:19]
	v_cndmask_b32_e64 v76, v251, 0, s[18:19]
	v_cndmask_b32_e64 v78, v252, 0, s[18:19]
	v_cndmask_b32_e64 v80, v253, 0, s[18:19]
	v_cndmask_b32_e64 v98, v21, v17, s[4:5]
	v_cndmask_b32_e64 v99, v20, v16, s[4:5]
	v_cndmask_b32_e64 v100, v19, v15, s[4:5]
	v_cndmask_b32_e64 v101, v18, v14, s[4:5]
	s_nop 1
	v_fmac_f32_dpp v26, v22, v74 row_ror:1 row_mask:0xf bank_mask:0xf
	s_nop 1
	v_fmac_f32_dpp v27, v23, v76 row_ror:1 row_mask:0xf bank_mask:0xf
	s_nop 1
	v_fmac_f32_dpp v28, v24, v78 row_ror:1 row_mask:0xf bank_mask:0xf
	s_nop 1
	v_fmac_f32_dpp v29, v25, v80 row_ror:1 row_mask:0xf bank_mask:0xf
	v_pk_fma_f32 v[24:25], v[16:17], v[210:211], v[198:199]
	v_pk_fma_f32 v[22:23], v[14:15], v[208:209], v[196:197]
	v_cndmask_b32_e32 v21, v17, v21, vcc
	v_cndmask_b32_e32 v20, v16, v20, vcc
	v_cndmask_b32_e32 v19, v15, v19, vcc
	v_cndmask_b32_e32 v18, v14, v18, vcc
	v_cndmask_b32_e64 v75, v212, 0, s[20:21]
	v_cndmask_b32_e64 v77, v213, 0, s[20:21]
	v_cndmask_b32_e64 v79, v214, 0, s[20:21]
	v_cndmask_b32_e64 v81, v215, 0, s[20:21]
	s_nop 1
	v_fmac_f32_dpp v26, v101, v75 row_ror:15 row_mask:0xf bank_mask:0xf
	s_nop 1
	v_fmac_f32_dpp v27, v100, v77 row_ror:15 row_mask:0xf bank_mask:0xf
	s_nop 1
	v_fmac_f32_dpp v28, v99, v79 row_ror:15 row_mask:0xf bank_mask:0xf
	s_nop 1
	v_fmac_f32_dpp v29, v98, v81 row_ror:15 row_mask:0xf bank_mask:0xf
	v_cndmask_b32_e64 v74, v250, 0, s[22:23]
	v_cndmask_b32_e64 v76, v251, 0, s[22:23]
;     DI void operator()(AccRef acc, const Unit& u, int wr, int wc, int fr, int fq) const {
;     ...
;             for (int bj = 0; bj < 2; ++bj) {
;                 const f32x4 w0 = *(const f32x4*)(cw + bj * DFF + cg_), w1 = *(const f32x4*)(cw + (size_t)2 * DFF + bj * DFF + cg_),
;                             w2 = *(const f32x4*)(cw + (size_t)4 * DFF + bj * DFF + cg_), wb = *(const f32x4*)(cb + bj * DFF + cg_);
; #pragma unroll
;                 for (int ai = 0; ai < 2; ++ai) {
;                     const int tok0 = 252 * u.pm - 1 + 126 * wr + 64 * ai;
; #pragma unroll
;                     for (int m = 0; m < 4; ++m) {
;                         const int tok = tok0 + 16 * m + fr; const int msk = tok < ML ? 4095 : 255;
;                         const bool hu = (tok & msk) != 0, hd = ((tok + 1) & msk) != 0;
;                         f32x4 r = acc[ai][bj][m][n] * w1 + wb;
;                         f32x4 w0m, w2m;
; #pragma unroll
;                         for (int j = 0; j < 4; ++j) { w0m[j] = hu ? w0[j] : 0.f; w2m[j] = hd ? w2[j] : 0.f; }
; #pragma unroll
;                         for (int j = 0; j < 4; ++j) {
;                             const float su = ((m > 0 || ai == 1) && fr == 15) ? (m > 0 ? acc[ai][bj][(m + 3) & 3][n][j] : acc[0][bj][3][n][j]) : acc[ai][bj][m][n][j];
;                             const float sd = ((m < 3 || ai == 0) && fr == 0) ? (m < 3 ? acc[ai][bj][(m + 1) & 3][n][j] : acc[1][bj][0][n][j]) : acc[ai][bj][m][n][j];
;                             float rj = r[j];
;                             asm("s_nop 1\n\tv_fmac_f32_dpp %0, %1, %2 row_ror:1 row_mask:0xf bank_mask:0xf" : "+v"(rj) : "v"(su), "v"(w0m[j]));
;                             asm("s_nop 1\n\tv_fmac_f32_dpp %0, %1, %2 row_ror:15 row_mask:0xf bank_mask:0xf" : "+v"(rj) : "v"(sd), "v"(w2m[j]));
;                             r[j] = rj; }
;                         if (bj == 0) {
; #pragma unroll
;                             for (int j = 0; j < 4; ++j) o[ai][m][j] = r[j] * __builtin_amdgcn_rcpf(1.f + __builtin_amdgcn_exp2f(-LOG2E * r[j]));
;                         } else o[ai][m] = o[ai][m] * r;
;                     }
;                 }
;             }
; #pragma unroll
;             for (int ai = 0; ai < 2; ++ai) {
;                 const int tok0 = 252 * u.pm - 1 + 126 * wr + 64 * ai;
; #pragma unroll
	v_cndmask_b32_e64 v78, v252, 0, s[22:23]
	v_cndmask_b32_e64 v80, v253, 0, s[22:23]
	v_cndmask_b32_e64 v98, v17, v13, s[4:5]
	v_cndmask_b32_e64 v99, v16, v12, s[4:5]
	v_cndmask_b32_e64 v100, v15, v11, s[4:5]
	v_cndmask_b32_e64 v101, v14, v10, s[4:5]
	s_nop 1
	v_fmac_f32_dpp v22, v18, v74 row_ror:1 row_mask:0xf bank_mask:0xf
	s_nop 1
	v_fmac_f32_dpp v23, v19, v76 row_ror:1 row_mask:0xf bank_mask:0xf
	s_nop 1
	v_fmac_f32_dpp v24, v20, v78 row_ror:1 row_mask:0xf bank_mask:0xf
	s_nop 1
	v_fmac_f32_dpp v25, v21, v80 row_ror:1 row_mask:0xf bank_mask:0xf
	v_pk_fma_f32 v[20:21], v[12:13], v[210:211], v[198:199]
	v_pk_fma_f32 v[18:19], v[10:11], v[208:209], v[196:197]
	v_cndmask_b32_e32 v17, v13, v17, vcc
	v_cndmask_b32_e32 v16, v12, v16, vcc
	v_cndmask_b32_e32 v15, v11, v15, vcc
	v_cndmask_b32_e32 v14, v10, v14, vcc
	v_cndmask_b32_e64 v75, v212, 0, s[24:25]
	v_cndmask_b32_e64 v77, v213, 0, s[24:25]
	v_cndmask_b32_e64 v79, v214, 0, s[24:25]
	v_cndmask_b32_e64 v81, v215, 0, s[24:25]
	s_nop 1
	v_fmac_f32_dpp v22, v101, v75 row_ror:15 row_mask:0xf bank_mask:0xf
	s_nop 1
	v_fmac_f32_dpp v23, v100, v77 row_ror:15 row_mask:0xf bank_mask:0xf
	s_nop 1
	v_fmac_f32_dpp v24, v99, v79 row_ror:15 row_mask:0xf bank_mask:0xf
	s_nop 1
	v_fmac_f32_dpp v25, v98, v81 row_ror:15 row_mask:0xf bank_mask:0xf
	v_cndmask_b32_e64 v74, v250, 0, s[26:27]
	v_cndmask_b32_e64 v76, v251, 0, s[26:27]
	v_cndmask_b32_e64 v78, v252, 0, s[26:27]
	v_cndmask_b32_e64 v80, v253, 0, s[26:27]
	v_cndmask_b32_e64 v98, v13, v9, s[4:5]
	v_cndmask_b32_e64 v99, v12, v8, s[4:5]
	v_cndmask_b32_e64 v100, v11, v7, s[4:5]
	v_cndmask_b32_e64 v101, v10, v6, s[4:5]
	s_nop 1
	v_fmac_f32_dpp v18, v14, v74 row_ror:1 row_mask:0xf bank_mask:0xf
	s_nop 1
	v_fmac_f32_dpp v19, v15, v76 row_ror:1 row_mask:0xf bank_mask:0xf
	s_nop 1
	v_fmac_f32_dpp v20, v16, v78 row_ror:1 row_mask:0xf bank_mask:0xf
	s_nop 1
	v_fmac_f32_dpp v21, v17, v80 row_ror:1 row_mask:0xf bank_mask:0xf
	v_pk_fma_f32 v[16:17], v[8:9], v[210:211], v[198:199]
	v_pk_fma_f32 v[14:15], v[6:7], v[208:209], v[196:197]
	v_cndmask_b32_e32 v13, v9, v13, vcc
	v_cndmask_b32_e32 v12, v8, v12, vcc
	v_cndmask_b32_e32 v11, v7, v11, vcc
	v_cndmask_b32_e32 v10, v6, v10, vcc
	v_cndmask_b32_e64 v74, v250, 0, s[36:37]
	v_cndmask_b32_e64 v76, v251, 0, s[36:37]
	v_cndmask_b32_e64 v78, v252, 0, s[36:37]
	v_cndmask_b32_e64 v80, v253, 0, s[36:37]
	s_nop 1
	v_fmac_f32_dpp v14, v10, v74 row_ror:1 row_mask:0xf bank_mask:0xf
	s_nop 1
	v_fmac_f32_dpp v15, v11, v76 row_ror:1 row_mask:0xf bank_mask:0xf
	s_nop 1
	v_fmac_f32_dpp v16, v12, v78 row_ror:1 row_mask:0xf bank_mask:0xf
	s_nop 1
	v_fmac_f32_dpp v17, v13, v80 row_ror:1 row_mask:0xf bank_mask:0xf
	v_pk_fma_f32 v[12:13], v[4:5], v[210:211], v[198:199]
	v_pk_fma_f32 v[10:11], v[2:3], v[208:209], v[196:197]
	v_cndmask_b32_e64 v75, v212, 0, s[30:31]
	v_cndmask_b32_e64 v77, v213, 0, s[30:31]
	v_cndmask_b32_e64 v79, v214, 0, s[30:31]
	v_cndmask_b32_e64 v81, v215, 0, s[30:31]
	s_nop 1
	v_fmac_f32_dpp v18, v101, v75 row_ror:15 row_mask:0xf bank_mask:0xf
	s_nop 1
	v_fmac_f32_dpp v19, v100, v77 row_ror:15 row_mask:0xf bank_mask:0xf
	s_nop 1
	v_fmac_f32_dpp v20, v99, v79 row_ror:15 row_mask:0xf bank_mask:0xf
	s_nop 1
	v_fmac_f32_dpp v21, v98, v81 row_ror:15 row_mask:0xf bank_mask:0xf
	v_cndmask_b32_e64 v98, v9, v5, s[4:5]
	v_cndmask_b32_e64 v99, v8, v4, s[4:5]
	v_cndmask_b32_e64 v100, v7, v3, s[4:5]
	v_cndmask_b32_e64 v101, v6, v2, s[4:5]
	v_cndmask_b32_e64 v38, v250, 0, s[28:29]
	v_cndmask_b32_e64 v39, v251, 0, s[28:29]
	v_cndmask_b32_e64 v40, v252, 0, s[28:29]
	v_cndmask_b32_e64 v41, v253, 0, s[28:29]
	v_cndmask_b32_e32 v9, v5, v9, vcc
	v_cndmask_b32_e32 v8, v4, v8, vcc
	v_cndmask_b32_e32 v7, v3, v7, vcc
	v_cndmask_b32_e32 v6, v2, v6, vcc
	s_nop 1
	v_fmac_f32_dpp v10, v6, v38 row_ror:1 row_mask:0xf bank_mask:0xf
	s_nop 1
	v_fmac_f32_dpp v11, v7, v39 row_ror:1 row_mask:0xf bank_mask:0xf
	s_nop 1
	v_fmac_f32_dpp v12, v8, v40 row_ror:1 row_mask:0xf bank_mask:0xf
	s_nop 1
	v_fmac_f32_dpp v13, v9, v41 row_ror:1 row_mask:0xf bank_mask:0xf
	v_cndmask_b32_e64 v75, v212, 0, s[38:39]
	v_cndmask_b32_e64 v77, v213, 0, s[38:39]
	v_cndmask_b32_e64 v79, v214, 0, s[38:39]
	v_cndmask_b32_e64 v81, v215, 0, s[38:39]
	s_nop 1
	v_fmac_f32_dpp v14, v101, v75 row_ror:15 row_mask:0xf bank_mask:0xf
	s_nop 1
	v_fmac_f32_dpp v15, v100, v77 row_ror:15 row_mask:0xf bank_mask:0xf
	s_nop 1
	v_fmac_f32_dpp v16, v99, v79 row_ror:15 row_mask:0xf bank_mask:0xf
	s_nop 1
	v_fmac_f32_dpp v17, v98, v81 row_ror:15 row_mask:0xf bank_mask:0xf
	v_cndmask_b32_e64 v42, v212, 0, s[34:35]
	v_cndmask_b32_e64 v43, v213, 0, s[34:35]
	v_cndmask_b32_e64 v44, v214, 0, s[34:35]
	v_cndmask_b32_e64 v45, v215, 0, s[34:35]
	s_nop 1
	v_fmac_f32_dpp v10, v2, v42 row_ror:15 row_mask:0xf bank_mask:0xf
	s_nop 1
	v_fmac_f32_dpp v11, v3, v43 row_ror:15 row_mask:0xf bank_mask:0xf
	s_nop 1
	v_fmac_f32_dpp v12, v4, v44 row_ror:15 row_mask:0xf bank_mask:0xf
	s_nop 1
	v_fmac_f32_dpp v13, v5, v45 row_ror:15 row_mask:0xf bank_mask:0xf
	s_and_saveexec_b64 s[0:1], s[54:55]
	s_cbranch_execz .LBB0_1626
	v_mul_f32_e32 v2, 0xbfb8aa3b, v84
	v_mul_f32_e32 v3, 0xbfb8aa3b, v85
	v_mul_f32_e32 v4, 0xbfb8aa3b, v82
	v_mul_f32_e32 v5, 0xbfb8aa3b, v83
	v_exp_f32_e32 v2, v2
	v_exp_f32_e32 v3, v3
	v_exp_f32_e32 v4, v4
	v_exp_f32_e32 v5, v5
	v_add_f32_e32 v2, 1.0, v2
	v_add_f32_e32 v3, 1.0, v3
	v_add_f32_e32 v4, 1.0, v4
	v_add_f32_e32 v5, 1.0, v5
	v_rcp_f32_e32 v2, v2
	v_rcp_f32_e32 v3, v3
	v_rcp_f32_e32 v4, v4
	v_rcp_f32_e32 v5, v5
	s_movk_i32 s4, 0x2c00
	v_pk_mul_f32 v[2:3], v[84:85], v[2:3]
	v_pk_mul_f32 v[4:5], v[82:83], v[4:5]
	s_nop 0
	v_pk_mul_f32 v[4:5], v[4:5], v[72:73]
	v_pk_mul_f32 v[2:3], v[2:3], v[70:71]
	s_nop 0
	v_cvt_pk_bf16_f32 v2, v2, v3
	v_cvt_pk_bf16_f32 v3, v4, v5
	v_mov_b64_e32 v[4:5], s[92:93]
	v_mad_i64_i32 v[4:5], s[4:5], v0, s4, v[4:5]
	v_lshl_add_u64 v[4:5], v[146:147], 1, v[4:5]
	global_store_dwordx2 v[4:5], v[2:3], off offset:8
	s_or_b64 exec, exec, s[0:1]
	s_and_saveexec_b64 s[0:1], s[74:75]
	s_cbranch_execnz .LBB0_1627
